# RG-LRU: sqrt(1-a^2) without the denormal-scale and class-select ops (operand is 0 or >= 2^-24; refinement kept, bit-identical), freed slots left as s_nop
# speedup vs baseline: 1.0028x; 1.0028x over previous
; #define LAS __attribute__((address_space(3)))
; DI float bf2f(unsigned h) { return __uint_as_float(h << 16); }
; DI float fexp2(float x) { return __builtin_amdgcn_exp2f(x); }
; DI float fsigmoid(float x) { return frcp(1.0f + fexp2(-LOG2E * x)); }
; DI void cv_issue_q(const CvJob& j, int idx, int lane, f32x4 (&v)[4], int r0) {
;     const float* W; int K, N, item; bf16* WT; const float* ks; cv_decode(j, idx, W, K, N, WT, ks, item);
;     const int nblk = N / 64, kb = item / nblk, nb = item % nblk, k0 = 64 * kb, n0 = 64 * nb, q = lane >> 4, c16 = lane & 15;
;     const char* ub = (const char*)(W + (size_t)(k0 + r0) * N + n0);
;     const unsigned vo = (unsigned)((16 * q) * N + 4 * c16) * 4u;
; #pragma unroll
;     for (int i = 0; i < 4; ++i) v[i] = *(const f32x4*)(ub + (size_t)i * N * 4 + vo);
; }
; DI void rglru_scan_unit(Frame& F, const Mix0Args& a, int u) {
;     ...
;         { bf16x8 xf[4], waf[4], wxf[4]; unsigned xcr[4];
; #pragma unroll
;           for (int ks = 0; ks < 4; ++ks) { xf[ks] = *(const LAS bf16x8*)(XCc + (l0_ + fr) * S128 + ks * 64 + fq * 16);
;               waf[ks] = *(const LAS bf16x8*)(WAT + (16 * jtile + fr) * S128 + ks * 64 + fq * 16); wxf[ks] = *(const LAS bf16x8*)(WXT + (16 * jtile + fr) * S128 + ks * 64 + fq * 16); }
; #pragma unroll
;           for (int r = 0; r < 4; ++r) xcr[r] = *(const LAS unsigned short*)(XCc + (l0_ + 4 * fq + r) * S128 + (qq * 32 + jj) * 2);
;           f32x4 R = zero4, I = zero4;
; #pragma unroll
;           for (int ks = 0; ks < 4; ++ks) { R = __builtin_amdgcn_mfma_f32_16x16x32_bf16(xf[ks], waf[ks], R, 0, 0, 0); I = __builtin_amdgcn_mfma_f32_16x16x32_bf16(xf[ks], wxf[ks], I, 0, 0, 0); }
; #pragma unroll
;           for (int r = 0; r < 4; ++r) {
;               const float rr = fsigmoid(R[r] + bav), ig = fsigmoid(I[r] + bxv);
;               const float aa = fexp2(-sp8l2 * rr); const float om = __builtin_fmaf(-aa, aa, 1.0f);
;               av[r] = aa; uv[r] = __builtin_sqrtf(om) * (ig * bf2f(xcr[r]));
;               Hseg = aa * Hseg + uv[r]; Aseg *= aa; } }
;         const int sgi = ltile * 4 + fq;
;         SEGA[jj * 20 + sgi] = Aseg; SEGH[jj * 20 + sgi] = Hseg;
.LBB0_269:
	s_lshr_b32 s79, s78, 6
	v_cvt_f32_u32_e32 v2, s79
	s_sub_i32 s90, 0, s79
	s_abs_i32 s89, s84
	s_ashr_i32 s88, s84, 31
	v_rcp_iflag_f32_e32 v2, v2
	v_mul_u32_u24_e32 v29, s78, v102
	v_or_b32_e32 v29, v29, v125
	v_lshlrev_b32_e32 v82, 2, v29
	v_mul_f32_e32 v2, 0x4f7ffffe, v2
	v_cvt_u32_f32_e32 v2, v2
	ds_read_b128 v[6:9], v103 offset:36864
	v_readfirstlane_b32 s91, v2
	s_mul_i32 s90, s90, s91
	s_mul_hi_u32 s90, s91, s90
	s_add_i32 s91, s91, s90
	s_mul_hi_u32 s90, s89, s91
	s_mul_i32 s91, s90, s79
	s_sub_i32 s89, s89, s91
	s_add_i32 vcc_lo, s90, 1
	s_sub_i32 s91, s89, s79
	s_cmp_ge_u32 s89, s79
	s_cselect_b32 s90, vcc_lo, s90
	s_cselect_b32 s89, s91, s89
	s_add_i32 s91, s90, 1
	ds_read_b128 v[2:5], v164
	s_cmp_ge_u32 s89, s79
	s_cselect_b32 s89, s91, s90
	s_xor_b32 s89, s89, s88
	s_sub_i32 s88, s89, s88
	s_mul_i32 s79, s88, s79
	s_lshl_b32 s88, s88, 6
	s_sub_i32 s79, s84, s79
	s_mul_hi_i32 s89, s88, s78
	s_mul_i32 s88, s88, s78
	s_lshl_b32 s90, s79, 6
	s_lshl_b64 s[88:89], s[88:89], 2
	s_add_u32 s79, s36, s88
	ds_read_b128 v[10:13], v103 offset:46080
	ds_read_b128 v[14:17], v164 offset:64
	ds_read_b128 v[30:33], v103 offset:36928
	ds_read_b128 v[38:41], v103 offset:46144
	ds_read_b128 v[42:45], v164 offset:128
	s_addc_u32 s84, s37, s89
	s_ashr_i32 s91, s90, 31
	s_waitcnt lgkmcnt(5)
	v_mfma_f32_16x16x32_bf16 v[6:9], v[2:5], v[6:9], 0
	s_lshl_b64 s[36:37], s[90:91], 2
	s_add_u32 s36, s79, s36
	s_addc_u32 s37, s84, s37
	s_waitcnt lgkmcnt(4)
	v_mfma_f32_16x16x32_bf16 v[10:13], v[2:5], v[10:13], 0
	global_load_dwordx4 v[2:5], v82, s[36:37]
	s_lshl_b32 s96, s78, 2
	v_lshl_add_u64 v[54:55], s[36:37], 0, v[82:83]
	s_waitcnt lgkmcnt(2)
	v_mfma_f32_16x16x32_bf16 v[6:9], v[14:17], v[30:33], v[6:9]
	ds_read_b128 v[30:33], v103 offset:36992
	ds_read_b128 v[46:49], v164 offset:192
	s_waitcnt lgkmcnt(3)
	v_mfma_f32_16x16x32_bf16 v[14:17], v[14:17], v[38:41], v[10:13]
	ds_read_b128 v[38:41], v103 offset:37056
	s_waitcnt lgkmcnt(2)
	v_mfma_f32_16x16x32_bf16 v[30:33], v[42:45], v[30:33], v[6:9]
	v_lshl_add_u64 v[10:11], v[54:55], 0, s[96:97]
	v_lshl_add_u64 v[58:59], v[10:11], 0, s[96:97]
	s_nop 0
	global_load_dwordx4 v[6:9], v[10:11], off
	s_nop 0
	global_load_dwordx4 v[10:13], v[58:59], off
	s_waitcnt lgkmcnt(0)
	v_mfma_f32_16x16x32_bf16 v[30:33], v[46:49], v[38:41], v[30:33]
	ds_read_b128 v[54:57], v103 offset:46208
	ds_read_b128 v[38:41], v103 offset:46272
	v_lshl_add_u64 v[58:59], v[58:59], 0, s[96:97]
	s_waitcnt lgkmcnt(1)
	v_mfma_f32_16x16x32_bf16 v[42:45], v[42:45], v[54:57], v[14:17]
	s_nop 2
	v_add_f32_e32 v29, v165, v30
	v_mul_f32_e32 v29, 0xbfb8aa3b, v29
	v_exp_f32_e32 v29, v29
	s_waitcnt lgkmcnt(0)
	v_mfma_f32_16x16x32_bf16 v[38:41], v[46:49], v[38:41], v[42:45]
	v_add_f32_e32 v31, v165, v31
	v_mul_f32_e32 v31, 0xbfb8aa3b, v31
	v_add_f32_e32 v14, 1.0, v29
	v_rcp_f32_e32 v29, v14
	v_exp_f32_e32 v31, v31
	global_load_dwordx4 v[14:17], v[58:59], off
	ds_read_u16 v42, v113
	ds_read_u16 v43, v113 offset:288
	ds_read_u16 v44, v113 offset:576
	ds_read_u16 v45, v113 offset:864
	v_mul_f32_e64 v29, v29, -v168
	v_exp_f32_e32 v70, v29
	v_add_f32_e32 v29, v167, v38
	v_mul_f32_e32 v29, 0xbfb8aa3b, v29
	v_exp_f32_e32 v29, v29
	v_fma_f32 v30, -v70, v70, 1.0
	s_nop 0
	s_nop 0
	v_add_f32_e32 v29, 1.0, v29
	v_rcp_f32_e32 v29, v29
	s_nop 0
	v_sqrt_f32_e32 v38, v30
	v_add_f32_e32 v31, 1.0, v31
	v_rcp_f32_e32 v31, v31
	v_add_f32_e32 v32, v165, v32
	v_add_u32_e32 v46, -1, v38
	v_fma_f32 v47, -v46, v38, v30
	v_cmp_ge_f32_e64 s[36:37], 0, v47
	v_add_u32_e32 v47, 1, v38
	v_mul_f32_e32 v32, 0xbfb8aa3b, v32
	v_cndmask_b32_e64 v46, v38, v46, s[36:37]
	v_fma_f32 v38, -v47, v38, v30
	v_cmp_lt_f32_e64 s[36:37], 0, v38
	v_exp_f32_e32 v32, v32
	v_add_f32_e32 v33, v165, v33
	v_cndmask_b32_e64 v38, v46, v47, s[36:37]
	s_nop 0
	s_nop 0
	s_nop 0
	v_add_f32_e32 v32, 1.0, v32
	v_rcp_f32_e32 v32, v32
	v_mov_b32_e32 v30, v38
	s_waitcnt lgkmcnt(3)
	v_lshlrev_b32_e32 v38, 16, v42
	v_mul_f32_e32 v29, v29, v38
	v_mul_f32_e32 v71, v29, v30
	v_mul_f32_e64 v29, v31, -v168
	v_exp_f32_e32 v72, v29
	v_add_f32_e32 v29, v167, v39
	v_mul_f32_e32 v29, 0xbfb8aa3b, v29
	v_exp_f32_e32 v29, v29
	v_fma_f32 v30, -v72, v72, 1.0
	s_nop 0
	s_nop 0
	v_add_f32_e32 v29, 1.0, v29
	v_rcp_f32_e32 v29, v29
	s_nop 0
	v_sqrt_f32_e32 v31, v30
	v_mul_f32_e32 v33, 0xbfb8aa3b, v33
	v_exp_f32_e32 v33, v33
	v_fma_f32 v38, 0, v70, v71
	v_add_u32_e32 v39, -1, v31
	v_fma_f32 v42, -v39, v31, v30
	v_cmp_ge_f32_e64 s[36:37], 0, v42
	v_add_u32_e32 v42, 1, v31
	v_add_f32_e32 v33, 1.0, v33
	v_cndmask_b32_e64 v39, v31, v39, s[36:37]
	v_fma_f32 v31, -v42, v31, v30
	v_cmp_lt_f32_e64 s[36:37], 0, v31
	v_rcp_f32_e32 v33, v33
	s_nop 0
	v_cndmask_b32_e64 v31, v39, v42, s[36:37]
	s_nop 0
	s_nop 0
	s_nop 0
	s_nop 1
	v_mov_b32_e32 v30, v31
	s_waitcnt lgkmcnt(2)
	v_lshlrev_b32_e32 v31, 16, v43
	v_mul_f32_e32 v29, v29, v31
	v_mul_f32_e32 v73, v29, v30
	v_mul_f32_e64 v30, v32, -v168
	v_exp_f32_e32 v74, v30
	v_add_f32_e32 v30, v167, v40
	v_mul_f32_e32 v30, 0xbfb8aa3b, v30
	v_exp_f32_e32 v30, v30
	v_fma_f32 v31, -v74, v74, 1.0
	s_nop 0
	s_nop 0
	v_add_f32_e32 v30, 1.0, v30
	v_rcp_f32_e32 v30, v30
	s_nop 0
	v_sqrt_f32_e32 v32, v31
	v_fma_f32 v29, v72, v38, v73
	v_mul_f32_e32 v38, v70, v72
	v_add_u32_e32 v39, -1, v32
	v_fma_f32 v40, -v39, v32, v31
	v_cmp_ge_f32_e64 s[36:37], 0, v40
	v_add_u32_e32 v40, 1, v32
	s_nop 0
	v_cndmask_b32_e64 v39, v32, v39, s[36:37]
	v_fma_f32 v32, -v40, v32, v31
	v_cmp_lt_f32_e64 s[36:37], 0, v32
	s_nop 1
	v_cndmask_b32_e64 v32, v39, v40, s[36:37]
	s_nop 0
	s_nop 0
	s_nop 0
	s_nop 1
	v_mov_b32_e32 v31, v32
	s_waitcnt lgkmcnt(1)
	v_lshlrev_b32_e32 v32, 16, v44
	v_mul_f32_e32 v30, v30, v32
	v_mul_f32_e32 v75, v30, v31
	v_fma_f32 v30, v74, v29, v75
	v_mul_f32_e64 v29, v33, -v168
	v_exp_f32_e32 v76, v29
	v_add_f32_e32 v29, v167, v41
	v_mul_f32_e32 v29, 0xbfb8aa3b, v29
	v_exp_f32_e32 v29, v29
	v_fma_f32 v31, -v76, v76, 1.0
	s_nop 0
	s_nop 0
	v_mul_f32_e32 v33, v74, v38
	v_add_f32_e32 v29, 1.0, v29
	s_nop 0
	v_sqrt_f32_e32 v32, v31
	v_rcp_f32_e32 v29, v29
	v_add_u32_e32 v38, -1, v32
	v_fma_f32 v39, -v38, v32, v31
	v_cmp_ge_f32_e64 s[36:37], 0, v39
	v_add_u32_e32 v39, 1, v32
	s_nop 0
	v_cndmask_b32_e64 v38, v32, v38, s[36:37]
	v_fma_f32 v32, -v39, v32, v31
	v_cmp_lt_f32_e64 s[36:37], 0, v32
	s_nop 1
	v_cndmask_b32_e64 v32, v38, v39, s[36:37]
	s_nop 0
	s_nop 0
	s_nop 0
	s_mov_b32 s36, 0x25300000
	s_nop 0
	v_mov_b32_e32 v31, v32
	s_waitcnt lgkmcnt(0)
	v_lshlrev_b32_e32 v32, 16, v45
	v_mul_f32_e32 v29, v29, v32
	v_mul_f32_e32 v29, v29, v31
	v_fma_f32 v30, v76, v30, v29
	v_mul_f32_e32 v31, v76, v33
	ds_write2st64_b32 v150, v31, v30 offset0:216 offset1:226
	s_waitcnt lgkmcnt(0)
	s_barrier
; #define LAS __attribute__((address_space(3)))
; DI float bf2f(unsigned h) { return __uint_as_float(h << 16); }
; DI unsigned pk2(float lo, float hi) { f32x2 v = {lo, hi}; bf16v2 b = __builtin_convertvector(v, bf16v2); return __builtin_bit_cast(unsigned, b); }
; DI float fsilu(float x) { return x * fsigmoid(x); }
; DI void rglru_scan_unit(Frame& F, const Mix0Args& a, int u) {
;     ...
;         float carry = HPREV[jj * 20 + (n & 1)]; float sa[15], sh[15];
;         { f32x4 a4[4], h4[4];
; #pragma unroll
;           for (int i = 0; i < 4; ++i) { a4[i] = *(const LAS f32x4*)(SEGA + jj * 20 + 4 * i); h4[i] = *(const LAS f32x4*)(SEGH + jj * 20 + 4 * i); }
; #pragma unroll
;           for (int s = 0; s < 15; ++s) { sa[s] = a4[s >> 2][s & 3]; sh[s] = h4[s >> 2][s & 3]; } }
; #pragma unroll
;         for (int s = 0; s < 15; ++s) carry = (s < sgi) ? sa[s] * carry + sh[s] : carry;
; #pragma unroll
;         for (int r = 0; r < 4; ++r) { carry = av[r] * carry + uv[r];
;             const float o = carry * fsilu(bf2f(gb_cur[r]));
;             obcol[(row0 + l0_ + 4 * fq + r) * a.out_ld] = (bf16)(pk2(o, 0.f) & 0xffffu); }
;         if (sgi == 15) HPREV[jj * 20 + ((n + 1) & 1)] = carry;
	ds_read_b32 v77, v149 offset:55360
	ds_read_b128 v[30:33], v149 offset:57856
	ds_read_b128 v[38:41], v149 offset:57872
	ds_read_b128 v[42:45], v149 offset:57888
	ds_read_b128 v[46:49], v149 offset:55296
	ds_read_b128 v[54:57], v149 offset:55312
	ds_read_b128 v[58:61], v149 offset:55328
	ds_read_b128 v[62:65], v149 offset:55344
	ds_read_b128 v[66:69], v149 offset:57904
	s_waitcnt lgkmcnt(4)
	v_fma_f32 v30, v77, v46, v30
	v_cndmask_b32_e64 v30, v30, v77, s[10:11]
	v_fma_f32 v31, v47, v30, v31
	v_cndmask_b32_e64 v30, v30, v31, s[12:13]
	v_fma_f32 v31, v48, v30, v32
	v_cndmask_b32_e64 v30, v30, v31, s[14:15]
	v_fmac_f32_e32 v33, v49, v30
	v_cndmask_b32_e64 v30, v33, v30, s[0:1]
	s_waitcnt lgkmcnt(3)
	v_fma_f32 v31, v54, v30, v38
	v_cndmask_b32_e64 v30, v30, v31, s[16:17]
	v_fma_f32 v31, v55, v30, v39
	v_cndmask_b32_e64 v30, v30, v31, s[18:19]
	v_fma_f32 v31, v56, v30, v40
	v_cndmask_b32_e64 v30, v30, v31, s[20:21]
	v_fmac_f32_e32 v41, v57, v30
	v_cndmask_b32_e64 v30, v30, v41, s[38:39]
	s_waitcnt lgkmcnt(2)
	v_fma_f32 v31, v58, v30, v42
	v_cndmask_b32_e64 v30, v30, v31, s[22:23]
	v_fma_f32 v31, v59, v30, v43
	v_cndmask_b32_e64 v30, v30, v31, s[24:25]
	v_fma_f32 v31, v60, v30, v44
	v_cndmask_b32_e64 v30, v30, v31, s[26:27]
	v_lshlrev_b32_e32 v32, 16, v181
	v_fmac_f32_e32 v45, v61, v30
	v_mul_f32_e32 v33, 0xbfb8aa3b, v32
	v_cndmask_b32_e64 v30, v30, v45, s[4:5]
	v_exp_f32_e32 v33, v33
	s_waitcnt lgkmcnt(0)
	v_fma_f32 v31, v62, v30, v66
	v_cndmask_b32_e64 v30, v30, v31, s[28:29]
	v_fma_f32 v31, v63, v30, v67
	v_cndmask_b32_e64 v30, v30, v31, s[30:31]
	v_add_f32_e32 v31, 1.0, v33
	v_rcp_f32_e32 v31, v31
	v_fmac_f32_e32 v68, v64, v30
	v_cndmask_b32_e64 v30, v30, v68, s[34:35]
	v_fmac_f32_e32 v71, v70, v30
	v_mul_f32_e32 v30, v31, v32
	v_mul_f32_e32 v30, v30, v71
	v_lshlrev_b32_e32 v33, 16, v180
	v_cvt_pk_bf16_f32 v32, v30, s0
	v_mul_f32_e32 v30, 0xbfb8aa3b, v33
	v_exp_f32_e32 v38, v30
	v_lshl_add_u64 v[66:67], v[116:117], 0, s[8:9]
	v_add_co_u32_e32 v30, vcc, s36, v66
	v_fmac_f32_e32 v73, v72, v71
	s_nop 0
	v_addc_co_u32_e32 v31, vcc, 0, v67, vcc
	global_store_short v[30:31], v32, off
	v_add_f32_e32 v30, 1.0, v38
	v_rcp_f32_e32 v30, v30
	v_lshlrev_b32_e32 v32, 16, v179
	v_mul_f32_e32 v31, 0xbfb8aa3b, v32
	v_exp_f32_e32 v31, v31
	v_mul_f32_e32 v30, v30, v33
	v_mul_f32_e32 v30, v30, v73
	v_cvt_pk_bf16_f32 v33, v30, s0
	v_add_f32_e32 v30, 1.0, v31
	v_rcp_f32_e32 v38, v30
	s_mov_b32 s36, 0x2530c000
	v_add_co_u32_e32 v30, vcc, s36, v66
	v_fmac_f32_e32 v75, v74, v73
	s_nop 0
	v_addc_co_u32_e32 v31, vcc, 0, v67, vcc
	global_store_short v[30:31], v33, off
	v_mul_f32_e32 v30, v38, v32
	v_lshlrev_b32_e32 v32, 16, v178
	v_mul_f32_e32 v31, 0xbfb8aa3b, v32
	v_exp_f32_e32 v31, v31
	v_mul_f32_e32 v30, v30, v75
	s_mov_b32 s36, 0x25318000
	v_cvt_pk_bf16_f32 v33, v30, s0
	v_add_f32_e32 v31, 1.0, v31
	v_rcp_f32_e32 v38, v31
	v_add_co_u32_e32 v30, vcc, s36, v66
	v_fmac_f32_e32 v29, v76, v75
	s_nop 0
	v_addc_co_u32_e32 v31, vcc, 0, v67, vcc
	global_store_short v[30:31], v33, off
	v_mul_f32_e32 v30, v38, v32
	v_mul_f32_e32 v30, v30, v29
	v_cvt_pk_bf16_f32 v32, v30, s0
	s_mov_b64 s[100:101], 0x25324000
	v_lshl_add_u64 v[30:31], v[66:67], 0, s[100:101]
	global_store_short v[30:31], v32, off
	s_and_saveexec_b64 s[36:37], s[34:35]
	ds_write_b32 v149, v29 offset:55364
	s_or_b64 exec, exec, s[36:37]
	s_waitcnt vmcnt(22)
	v_lshlrev_b32_e32 v30, 16, v18
	v_and_b32_e32 v31, 0xffff0000, v18
	v_pk_fma_f32 v[30:31], v[104:105], v[30:31], v[100:101]
	s_waitcnt vmcnt(21)
	v_lshlrev_b32_e32 v18, 16, v19
	v_and_b32_e32 v19, 0xffff0000, v19
	v_pk_fma_f32 v[30:31], v[106:107], v[18:19], v[30:31]
	s_waitcnt vmcnt(20)
	v_lshlrev_b32_e32 v32, 16, v20
	v_and_b32_e32 v33, 0xffff0000, v20
	v_pk_fma_f32 v[30:31], v[108:109], v[32:33], v[30:31]
	s_waitcnt vmcnt(19)
	v_lshlrev_b32_e32 v20, 16, v21
	v_and_b32_e32 v21, 0xffff0000, v21
	v_pk_fma_f32 v[18:19], v[104:105], v[18:19], v[100:101]
	v_pk_fma_f32 v[30:31], v[110:111], v[20:21], v[30:31]
	v_pk_fma_f32 v[18:19], v[106:107], v[32:33], v[18:19]
	v_cvt_pk_bf16_f32 v29, v30, v31
	v_pk_fma_f32 v[18:19], v[108:109], v[20:21], v[18:19]
	s_waitcnt vmcnt(18)
	v_lshlrev_b32_e32 v30, 16, v22
	v_and_b32_e32 v31, 0xffff0000, v22
	v_pk_fma_f32 v[18:19], v[110:111], v[30:31], v[18:19]
	s_waitcnt vmcnt(17)
	v_lshlrev_b32_e32 v22, 16, v23
	v_cvt_pk_bf16_f32 v18, v18, v19
	ds_write2_b32 v123, v29, v18 offset1:72
	v_pk_fma_f32 v[18:19], v[104:105], v[32:33], v[100:101]
	v_and_b32_e32 v23, 0xffff0000, v23
	v_pk_fma_f32 v[18:19], v[106:107], v[20:21], v[18:19]
	v_add_u32_e32 v54, 0x400, v123
	v_pk_fma_f32 v[18:19], v[108:109], v[30:31], v[18:19]
	s_mov_b32 s36, 0x25be4000
	v_pk_fma_f32 v[18:19], v[110:111], v[22:23], v[18:19]
	s_nop 0
	v_cvt_pk_bf16_f32 v29, v18, v19
	v_pk_fma_f32 v[18:19], v[104:105], v[20:21], v[100:101]
	s_waitcnt vmcnt(16)
	v_lshlrev_b32_e32 v20, 16, v24
	v_pk_fma_f32 v[18:19], v[106:107], v[30:31], v[18:19]
	v_and_b32_e32 v21, 0xffff0000, v24
	v_pk_fma_f32 v[18:19], v[108:109], v[22:23], v[18:19]
	s_nop 0
	v_pk_fma_f32 v[18:19], v[110:111], v[20:21], v[18:19]
	s_nop 0
	v_cvt_pk_bf16_f32 v18, v18, v19
	ds_write2_b32 v123, v29, v18 offset0:144 offset1:216
	v_pk_fma_f32 v[18:19], v[104:105], v[30:31], v[100:101]
	s_waitcnt vmcnt(15)
	v_lshlrev_b32_e32 v30, 16, v27
	v_pk_fma_f32 v[18:19], v[106:107], v[22:23], v[18:19]
	v_and_b32_e32 v31, 0xffff0000, v27
	v_pk_fma_f32 v[18:19], v[108:109], v[20:21], v[18:19]
	s_nop 0
	v_pk_fma_f32 v[18:19], v[110:111], v[30:31], v[18:19]
	s_nop 0
	v_cvt_pk_bf16_f32 v24, v18, v19
	v_pk_fma_f32 v[18:19], v[104:105], v[22:23], v[100:101]
	s_waitcnt vmcnt(14)
	v_lshlrev_b32_e32 v22, 16, v25
	v_pk_fma_f32 v[18:19], v[106:107], v[20:21], v[18:19]
	v_and_b32_e32 v23, 0xffff0000, v25
	v_pk_fma_f32 v[18:19], v[108:109], v[30:31], v[18:19]
	s_nop 0
	v_pk_fma_f32 v[18:19], v[110:111], v[22:23], v[18:19]
	s_nop 0
	v_cvt_pk_bf16_f32 v18, v18, v19
	ds_write2_b32 v54, v24, v18 offset0:32 offset1:104
	v_pk_fma_f32 v[18:19], v[104:105], v[20:21], v[100:101]
	s_waitcnt vmcnt(13)
	v_lshlrev_b32_e32 v20, 16, v26
	v_pk_fma_f32 v[18:19], v[106:107], v[30:31], v[18:19]
	v_and_b32_e32 v21, 0xffff0000, v26
	v_pk_fma_f32 v[18:19], v[108:109], v[22:23], v[18:19]
	s_nop 0
	v_pk_fma_f32 v[18:19], v[110:111], v[20:21], v[18:19]
	s_nop 0
	v_cvt_pk_bf16_f32 v24, v18, v19
	v_pk_fma_f32 v[18:19], v[104:105], v[30:31], v[100:101]
	s_nop 0
	v_pk_fma_f32 v[18:19], v[106:107], v[22:23], v[18:19]
	s_nop 0
	v_pk_fma_f32 v[18:19], v[108:109], v[20:21], v[18:19]
	s_waitcnt vmcnt(12)
	v_lshlrev_b32_e32 v20, 16, v28
	v_and_b32_e32 v21, 0xffff0000, v28
	v_pk_fma_f32 v[18:19], v[110:111], v[20:21], v[18:19]
	s_nop 0
	v_cvt_pk_bf16_f32 v18, v18, v19
	ds_write2_b32 v54, v24, v18 offset0:176 offset1:248
	v_add_co_u32_e32 v18, vcc, s36, v50
	s_mov_b32 s36, 0x25bf0000
	s_nop 0
	v_addc_co_u32_e32 v19, vcc, 0, v51, vcc
	global_load_dword v130, v[18:19], off
	v_add_co_u32_e32 v18, vcc, s36, v50
	s_mov_b32 s36, 0x25bfc000
	s_nop 0
	v_addc_co_u32_e32 v19, vcc, 0, v51, vcc
	global_load_dword v132, v[18:19], off
	v_add_co_u32_e32 v18, vcc, s36, v50
	s_mov_b32 s36, 0x25c08000
	s_nop 0
	v_addc_co_u32_e32 v19, vcc, 0, v51, vcc
	global_load_dword v134, v[18:19], off
	v_add_co_u32_e32 v18, vcc, s36, v50
	s_mov_b32 s36, 0x25c14000
	s_nop 0
	v_addc_co_u32_e32 v19, vcc, 0, v51, vcc
	global_load_dword v169, v[18:19], off
	v_add_co_u32_e32 v18, vcc, s36, v50
	s_mov_b32 s36, 0x25c20000
	s_nop 0
	v_addc_co_u32_e32 v19, vcc, 0, v51, vcc
	global_load_dword v170, v[18:19], off
	v_add_co_u32_e32 v18, vcc, s36, v50
	s_mov_b32 s36, 0x25c2c000
	s_nop 0
	v_addc_co_u32_e32 v19, vcc, 0, v51, vcc
	global_load_dword v171, v[18:19], off
	v_add_co_u32_e32 v18, vcc, s36, v50
	s_mov_b32 s36, 0x25c38000
	s_nop 0
	v_addc_co_u32_e32 v19, vcc, 0, v51, vcc
	global_load_dword v172, v[18:19], off
	v_add_co_u32_e32 v18, vcc, s36, v50
	s_mov_b32 s36, 0x25c44000
	s_nop 0
	v_addc_co_u32_e32 v19, vcc, 0, v51, vcc
	global_load_dword v173, v[18:19], off
	v_add_co_u32_e32 v18, vcc, s36, v50
	s_mov_b32 s36, 0x25c50000
	s_nop 0
	v_addc_co_u32_e32 v19, vcc, 0, v51, vcc
	global_load_dword v174, v[18:19], off
	v_add_co_u32_e32 v18, vcc, s36, v50
	s_mov_b32 s36, 0x25c5c000
	s_nop 0
	v_addc_co_u32_e32 v19, vcc, 0, v51, vcc
	global_load_dword v175, v[18:19], off
	v_add_co_u32_e32 v18, vcc, s36, v50
	s_mov_b32 s36, 0x2590a000
	s_nop 0
	v_addc_co_u32_e32 v19, vcc, 0, v51, vcc
	global_load_dword v176, v[18:19], off
	v_add_co_u32_e32 v18, vcc, s36, v52
	s_nop 1
	v_addc_co_u32_e32 v19, vcc, 0, v53, vcc
	global_load_ushort v58, v[18:19], off
	s_mov_b64 s[100:101], 0x25916000
	v_lshl_add_u64 v[18:19], v[52:53], 0, s[100:101]
	global_load_ushort v56, v[18:19], off
	s_mov_b64 s[100:101], 0x25922000
	v_lshl_add_u64 v[18:19], v[52:53], 0, s[100:101]
	global_load_ushort v55, v[18:19], off
	s_mov_b64 s[100:101], 0x2592e000
	v_lshl_add_u64 v[18:19], v[52:53], 0, s[100:101]
	global_load_ushort v57, v[18:19], off
	v_cndmask_b32_e64 v18, 0, 1, s[40:41]
	v_cmp_ne_u32_e64 s[36:37], 1, v18
	s_andn2_b64 vcc, exec, s[40:41]
	s_cbranch_vccnz .LBB0_274
	s_cmpk_gt_u32 s87, 0x687f
	s_cbranch_scc0 .LBB0_275
	s_add_i32 s84, s87, 0xffff9780
	s_mov_b64 s[40:41], s[52:53]
	s_movk_i32 s78, 0x1000
	s_cbranch_execz .LBB0_276
	s_branch .LBB0_277

; #define LAS __attribute__((address_space(3)))
; DI float bf2f(unsigned h) { return __uint_as_float(h << 16); }
; DI float fexp2(float x) { return __builtin_amdgcn_exp2f(x); }
; DI float fsigmoid(float x) { return frcp(1.0f + fexp2(-LOG2E * x)); }
; DI void cv_issue_q(const CvJob& j, int idx, int lane, f32x4 (&v)[4], int r0) {
;     const float* W; int K, N, item; bf16* WT; const float* ks; cv_decode(j, idx, W, K, N, WT, ks, item);
;     const int nblk = N / 64, kb = item / nblk, nb = item % nblk, k0 = 64 * kb, n0 = 64 * nb, q = lane >> 4, c16 = lane & 15;
;     const char* ub = (const char*)(W + (size_t)(k0 + r0) * N + n0);
;     const unsigned vo = (unsigned)((16 * q) * N + 4 * c16) * 4u;
; #pragma unroll
;     for (int i = 0; i < 4; ++i) v[i] = *(const f32x4*)(ub + (size_t)i * N * 4 + vo);
; }
; DI void rglru_scan_unit(Frame& F, const Mix0Args& a, int u) {
;     ...
;         { bf16x8 xf[4], waf[4], wxf[4]; unsigned xcr[4];
; #pragma unroll
;           for (int ks = 0; ks < 4; ++ks) { xf[ks] = *(const LAS bf16x8*)(XCc + (l0_ + fr) * S128 + ks * 64 + fq * 16);
;               waf[ks] = *(const LAS bf16x8*)(WAT + (16 * jtile + fr) * S128 + ks * 64 + fq * 16); wxf[ks] = *(const LAS bf16x8*)(WXT + (16 * jtile + fr) * S128 + ks * 64 + fq * 16); }
; #pragma unroll
;           for (int r = 0; r < 4; ++r) xcr[r] = *(const LAS unsigned short*)(XCc + (l0_ + 4 * fq + r) * S128 + (qq * 32 + jj) * 2);
;           f32x4 R = zero4, I = zero4;
; #pragma unroll
;           for (int ks = 0; ks < 4; ++ks) { R = __builtin_amdgcn_mfma_f32_16x16x32_bf16(xf[ks], waf[ks], R, 0, 0, 0); I = __builtin_amdgcn_mfma_f32_16x16x32_bf16(xf[ks], wxf[ks], I, 0, 0, 0); }
; #pragma unroll
;           for (int r = 0; r < 4; ++r) {
;               const float rr = fsigmoid(R[r] + bav), ig = fsigmoid(I[r] + bxv);
;               const float aa = fexp2(-sp8l2 * rr); const float om = __builtin_fmaf(-aa, aa, 1.0f);
;               av[r] = aa; uv[r] = __builtin_sqrtf(om) * (ig * bf2f(xcr[r]));
;               Hseg = aa * Hseg + uv[r]; Aseg *= aa; } }
;         const int sgi = ltile * 4 + fq;
;         SEGA[jj * 20 + sgi] = Aseg; SEGH[jj * 20 + sgi] = Hseg;
.LBB0_277:
	s_lshr_b32 s79, s78, 6
	v_cvt_f32_u32_e32 v18, s79
	s_sub_i32 s90, 0, s79
	s_abs_i32 s89, s84
	s_ashr_i32 s88, s84, 31
	v_rcp_iflag_f32_e32 v18, v18
	v_mul_u32_u24_e32 v42, s78, v102
	v_or_b32_e32 v42, v42, v125
	v_lshlrev_b32_e32 v82, 2, v42
	v_mul_f32_e32 v18, 0x4f7ffffe, v18
	v_cvt_u32_f32_e32 v18, v18
	s_waitcnt vmcnt(26)
	v_lshlrev_b32_e32 v37, 16, v37
	s_waitcnt vmcnt(24)
	v_lshlrev_b32_e32 v34, 16, v34
	ds_read_b128 v[22:25], v103 offset:36864
	v_readfirstlane_b32 s91, v18
	s_mul_i32 s90, s90, s91
	s_mul_hi_u32 s90, s91, s90
	s_add_i32 s91, s91, s90
	s_mul_hi_u32 s90, s89, s91
	s_mul_i32 s91, s90, s79
	s_sub_i32 s89, s89, s91
	s_add_i32 vcc_lo, s90, 1
	s_sub_i32 s91, s89, s79
	s_cmp_ge_u32 s89, s79
	s_cselect_b32 s90, vcc_lo, s90
	s_cselect_b32 s89, s91, s89
	s_add_i32 s91, s90, 1
	s_cmp_ge_u32 s89, s79
	ds_read_b128 v[18:21], v164 offset:18432
	s_cselect_b32 s89, s91, s90
	s_xor_b32 s89, s89, s88
	s_sub_i32 s88, s89, s88
	s_mul_i32 s79, s88, s79
	s_lshl_b32 s88, s88, 6
	s_sub_i32 s79, s84, s79
	s_or_b32 s84, s88, 4
	s_mul_hi_i32 s91, s84, s78
	s_mul_i32 s90, s84, s78
	s_lshl_b32 s88, s79, 6
	s_lshl_b64 s[90:91], s[90:91], 2
	s_add_u32 s79, s40, s90
	ds_read_b128 v[26:29], v103 offset:46080
	ds_read_b128 v[30:33], v164 offset:18496
	ds_read_b128 v[38:41], v103 offset:36928
	ds_read_b128 v[42:45], v103 offset:46144
	ds_read_b128 v[46:49], v164 offset:18560
	s_addc_u32 s84, s41, s91
	s_ashr_i32 s89, s88, 31
	s_waitcnt lgkmcnt(5)
	v_mfma_f32_16x16x32_bf16 v[22:25], v[18:21], v[22:25], 0
	s_lshl_b64 s[40:41], s[88:89], 2
	s_add_u32 s40, s79, s40
	s_addc_u32 s41, s84, s41
	s_waitcnt lgkmcnt(4)
	v_mfma_f32_16x16x32_bf16 v[26:29], v[18:21], v[26:29], 0
	global_load_dwordx4 v[18:21], v82, s[40:41]
	s_lshl_b32 s96, s78, 2
	v_lshl_add_u64 v[64:65], s[40:41], 0, v[82:83]
	s_waitcnt lgkmcnt(2)
	v_mfma_f32_16x16x32_bf16 v[22:25], v[30:33], v[38:41], v[22:25]
	ds_read_b128 v[38:41], v103 offset:36992
	ds_read_b128 v[60:63], v164 offset:18624
	s_waitcnt lgkmcnt(3)
	v_mfma_f32_16x16x32_bf16 v[30:33], v[30:33], v[42:45], v[26:29]
	ds_read_b128 v[42:45], v103 offset:37056
	s_waitcnt lgkmcnt(2)
	v_mfma_f32_16x16x32_bf16 v[38:41], v[46:49], v[38:41], v[22:25]
	v_lshl_add_u64 v[26:27], v[64:65], 0, s[96:97]
	v_lshl_add_u64 v[64:65], v[26:27], 0, s[96:97]
	s_nop 0
	global_load_dwordx4 v[22:25], v[26:27], off
	s_nop 0
	global_load_dwordx4 v[26:29], v[64:65], off
	s_waitcnt lgkmcnt(0)
	v_mfma_f32_16x16x32_bf16 v[38:41], v[60:63], v[42:45], v[38:41]
	ds_read_b128 v[68:71], v103 offset:46208
	ds_read_b128 v[42:45], v103 offset:46272
	v_lshl_add_u64 v[64:65], v[64:65], 0, s[96:97]
	s_waitcnt lgkmcnt(1)
	v_mfma_f32_16x16x32_bf16 v[46:49], v[46:49], v[68:71], v[30:33]
	s_nop 2
	v_add_f32_e32 v38, v165, v38
	v_mul_f32_e32 v38, 0xbfb8aa3b, v38
	v_exp_f32_e32 v38, v38
	s_waitcnt lgkmcnt(0)
	v_mfma_f32_16x16x32_bf16 v[42:45], v[60:63], v[42:45], v[46:49]
	v_add_f32_e32 v39, v165, v39
	v_mul_f32_e32 v39, 0xbfb8aa3b, v39
	v_add_f32_e32 v30, 1.0, v38
	v_rcp_f32_e32 v38, v30
	v_exp_f32_e32 v39, v39
	global_load_dwordx4 v[30:33], v[64:65], off
	ds_read_u16 v47, v177 offset:18432
	ds_read_u16 v49, v177 offset:18720
	ds_read_u16 v59, v177 offset:19008
	ds_read_u16 v60, v177 offset:19296
	v_mul_f32_e64 v38, v38, -v168
	v_exp_f32_e32 v48, v38
	v_add_f32_e32 v38, v167, v42
	v_mul_f32_e32 v38, 0xbfb8aa3b, v38
	v_exp_f32_e32 v38, v38
	v_fma_f32 v42, -v48, v48, 1.0
	s_nop 0
	s_nop 0
	v_add_f32_e32 v38, 1.0, v38
	v_rcp_f32_e32 v38, v38
	s_nop 0
	v_sqrt_f32_e32 v46, v42
	v_add_f32_e32 v39, 1.0, v39
	v_rcp_f32_e32 v39, v39
	v_add_f32_e32 v40, v165, v40
	v_add_u32_e32 v61, -1, v46
	v_fma_f32 v62, -v61, v46, v42
	v_cmp_ge_f32_e64 s[40:41], 0, v62
	v_add_u32_e32 v62, 1, v46
	v_mul_f32_e32 v40, 0xbfb8aa3b, v40
	v_cndmask_b32_e64 v61, v46, v61, s[40:41]
	v_fma_f32 v46, -v62, v46, v42
	v_cmp_lt_f32_e64 s[40:41], 0, v46
	v_exp_f32_e32 v40, v40
	v_add_f32_e32 v41, v165, v41
	v_cndmask_b32_e64 v46, v61, v62, s[40:41]
	s_nop 0
	s_nop 0
	s_nop 0
	v_add_f32_e32 v40, 1.0, v40
	v_rcp_f32_e32 v40, v40
	v_mov_b32_e32 v42, v46
	s_waitcnt lgkmcnt(3)
	v_lshlrev_b32_e32 v46, 16, v47
	v_mul_f32_e32 v38, v38, v46
	v_mul_f32_e32 v64, v38, v42
	v_mul_f32_e64 v38, v39, -v168
	v_exp_f32_e32 v39, v38
	v_add_f32_e32 v38, v167, v43
	v_mul_f32_e32 v38, 0xbfb8aa3b, v38
	v_exp_f32_e32 v38, v38
	v_fma_f32 v42, -v39, v39, 1.0
	s_nop 0
	s_nop 0
	v_add_f32_e32 v38, 1.0, v38
	v_rcp_f32_e32 v38, v38
	s_nop 0
	v_sqrt_f32_e32 v43, v42
	v_mul_f32_e64 v40, v40, -v168
	v_exp_f32_e32 v65, v40
	v_add_f32_e32 v40, v167, v44
	v_add_u32_e32 v47, -1, v43
	v_fma_f32 v61, -v47, v43, v42
	v_cmp_ge_f32_e64 s[40:41], 0, v61
	v_add_u32_e32 v61, 1, v43
	v_fma_f32 v46, 0, v48, v64
	v_cndmask_b32_e64 v47, v43, v47, s[40:41]
	v_fma_f32 v43, -v61, v43, v42
	v_cmp_lt_f32_e64 s[40:41], 0, v43
	v_mul_f32_e32 v40, 0xbfb8aa3b, v40
	v_exp_f32_e32 v40, v40
	v_cndmask_b32_e64 v43, v47, v61, s[40:41]
	s_nop 0
	s_nop 0
	s_nop 0
	v_mul_f32_e32 v41, 0xbfb8aa3b, v41
	v_exp_f32_e32 v41, v41
	v_mov_b32_e32 v42, v43
	s_waitcnt lgkmcnt(2)
	v_lshlrev_b32_e32 v43, 16, v49
	v_mul_f32_e32 v38, v38, v43
	v_mul_f32_e32 v49, v38, v42
	v_fma_f32 v42, -v65, v65, 1.0
	s_nop 0
	s_nop 0
	v_fma_f32 v38, v39, v46, v49
	v_add_f32_e32 v40, 1.0, v40
	s_nop 0
	v_sqrt_f32_e32 v43, v42
	v_rcp_f32_e32 v40, v40
	v_add_f32_e32 v41, 1.0, v41
	v_rcp_f32_e32 v41, v41
	v_add_u32_e32 v46, -1, v43
	v_fma_f32 v47, -v46, v43, v42
	v_cmp_ge_f32_e64 s[40:41], 0, v47
	v_add_u32_e32 v47, 1, v43
	v_mul_f32_e32 v44, v48, v39
	v_cndmask_b32_e64 v46, v43, v46, s[40:41]
	v_fma_f32 v43, -v47, v43, v42
	v_cmp_lt_f32_e64 s[40:41], 0, v43
	s_nop 1
	v_cndmask_b32_e64 v43, v46, v47, s[40:41]
	s_nop 0
	s_nop 0
	s_nop 0
	s_nop 1
	v_mov_b32_e32 v42, v43
	s_waitcnt lgkmcnt(1)
	v_lshlrev_b32_e32 v43, 16, v59
	v_mul_f32_e32 v40, v40, v43
	v_mul_f32_e32 v59, v40, v42
	v_fma_f32 v40, v65, v38, v59
	v_mul_f32_e64 v38, v41, -v168
	v_exp_f32_e32 v80, v38
	v_add_f32_e32 v38, v167, v45
	v_mul_f32_e32 v38, 0xbfb8aa3b, v38
	v_exp_f32_e32 v38, v38
	v_fma_f32 v41, -v80, v80, 1.0
	s_nop 0
	s_nop 0
	v_mul_f32_e32 v43, v65, v44
	v_add_f32_e32 v38, 1.0, v38
	s_nop 0
	v_sqrt_f32_e32 v42, v41
	v_rcp_f32_e32 v38, v38
	v_add_u32_e32 v44, -1, v42
	v_fma_f32 v45, -v44, v42, v41
	v_cmp_ge_f32_e64 s[40:41], 0, v45
	v_add_u32_e32 v45, 1, v42
	s_nop 0
	v_cndmask_b32_e64 v44, v42, v44, s[40:41]
	v_fma_f32 v42, -v45, v42, v41
	v_cmp_lt_f32_e64 s[40:41], 0, v42
	s_nop 1
	v_cndmask_b32_e64 v42, v44, v45, s[40:41]
	s_nop 0
	s_nop 0
	s_nop 0
	s_mov_b32 s40, 0x25600000
	s_nop 0
	v_mov_b32_e32 v41, v42
	s_waitcnt lgkmcnt(0)
	v_lshlrev_b32_e32 v42, 16, v60
	v_mul_f32_e32 v38, v38, v42
	v_mul_f32_e32 v38, v38, v41
	v_fma_f32 v40, v80, v40, v38
	v_mul_f32_e32 v41, v80, v43
	ds_write2st64_b32 v150, v41, v40 offset0:236 offset1:246
	s_waitcnt lgkmcnt(0)
	s_barrier
; #define LAS __attribute__((address_space(3)))
; DI float bf2f(unsigned h) { return __uint_as_float(h << 16); }
; DI unsigned pk2(float lo, float hi) { f32x2 v = {lo, hi}; bf16v2 b = __builtin_convertvector(v, bf16v2); return __builtin_bit_cast(unsigned, b); }
; DI float fsilu(float x) { return x * fsigmoid(x); }
; DI void rglru_scan_unit(Frame& F, const Mix0Args& a, int u) {
;     ...
;         float carry = HPREV[jj * 20 + (n & 1)]; float sa[15], sh[15];
;         { f32x4 a4[4], h4[4];
; #pragma unroll
;           for (int i = 0; i < 4; ++i) { a4[i] = *(const LAS f32x4*)(SEGA + jj * 20 + 4 * i); h4[i] = *(const LAS f32x4*)(SEGH + jj * 20 + 4 * i); }
; #pragma unroll
;           for (int s = 0; s < 15; ++s) { sa[s] = a4[s >> 2][s & 3]; sh[s] = h4[s >> 2][s & 3]; } }
; #pragma unroll
;         for (int s = 0; s < 15; ++s) carry = (s < sgi) ? sa[s] * carry + sh[s] : carry;
; #pragma unroll
;         for (int r = 0; r < 4; ++r) { carry = av[r] * carry + uv[r];
;             const float o = carry * fsilu(bf2f(gb_cur[r]));
;             obcol[(row0 + l0_ + 4 * fq + r) * a.out_ld] = (bf16)(pk2(o, 0.f) & 0xffffu); }
;         if (sgi == 15) HPREV[jj * 20 + ((n + 1) & 1)] = carry;
	ds_read_b32 v81, v149 offset:55364
	ds_read_b128 v[40:43], v149 offset:60416
	ds_read_b128 v[44:47], v149 offset:62976
	ds_read_b128 v[60:63], v149 offset:60432
	ds_read_b128 v[68:71], v149 offset:60448
	ds_read_b128 v[72:75], v149 offset:62992
	ds_read_b128 v[76:79], v149 offset:63008
	ds_read_b128 v[178:181], v149 offset:60464
	ds_read_b128 v[184:187], v149 offset:63024
	s_waitcnt lgkmcnt(6)
	v_fma_f32 v40, v81, v40, v44
	v_cndmask_b32_e64 v40, v40, v81, s[10:11]
	v_fma_f32 v41, v41, v40, v45
	v_cndmask_b32_e64 v40, v40, v41, s[12:13]
	v_fma_f32 v41, v42, v40, v46
	v_cndmask_b32_e64 v40, v40, v41, s[14:15]
	v_fmac_f32_e32 v47, v43, v40
	v_cndmask_b32_e64 v40, v47, v40, s[0:1]
	s_waitcnt lgkmcnt(3)
	v_fma_f32 v41, v60, v40, v72
	v_cndmask_b32_e64 v40, v40, v41, s[16:17]
	v_fma_f32 v41, v61, v40, v73
	v_cndmask_b32_e64 v40, v40, v41, s[18:19]
	v_fma_f32 v41, v62, v40, v74
	v_cndmask_b32_e64 v40, v40, v41, s[20:21]
	v_fmac_f32_e32 v75, v63, v40
	v_cndmask_b32_e64 v40, v40, v75, s[38:39]
	s_waitcnt lgkmcnt(2)
	v_fma_f32 v41, v68, v40, v76
	v_cndmask_b32_e64 v40, v40, v41, s[22:23]
	v_fma_f32 v41, v69, v40, v77
	v_cndmask_b32_e64 v40, v40, v41, s[24:25]
	v_fma_f32 v41, v70, v40, v78
	v_cndmask_b32_e64 v40, v40, v41, s[26:27]
	v_fmac_f32_e32 v79, v71, v40
	v_mul_f32_e32 v42, 0xbfb8aa3b, v37
	v_cndmask_b32_e64 v40, v40, v79, s[4:5]
	v_exp_f32_e32 v42, v42
	s_waitcnt lgkmcnt(0)
	v_fma_f32 v41, v178, v40, v184
	v_cndmask_b32_e64 v40, v40, v41, s[28:29]
	v_fma_f32 v41, v179, v40, v185
	v_cndmask_b32_e64 v40, v40, v41, s[30:31]
	v_add_f32_e32 v41, 1.0, v42
	v_rcp_f32_e32 v41, v41
	v_fmac_f32_e32 v186, v180, v40
	v_cndmask_b32_e64 v40, v40, v186, s[34:35]
	v_fmac_f32_e32 v64, v48, v40
	v_mul_f32_e32 v37, v41, v37
	v_lshlrev_b32_e32 v41, 16, v36
	v_mul_f32_e32 v36, 0xbfb8aa3b, v41
	v_exp_f32_e32 v42, v36
	v_mul_f32_e32 v37, v37, v64
	v_add_co_u32_e32 v36, vcc, s40, v66
	v_cvt_pk_bf16_f32 v40, v37, s0
	s_nop 0
	v_addc_co_u32_e32 v37, vcc, 0, v67, vcc
	global_store_short v[36:37], v40, off
	v_add_f32_e32 v36, 1.0, v42
	v_rcp_f32_e32 v36, v36
	v_mul_f32_e32 v37, 0xbfb8aa3b, v34
	v_exp_f32_e32 v37, v37
	v_fmac_f32_e32 v49, v39, v64
	v_mul_f32_e32 v36, v36, v41
	v_mul_f32_e32 v36, v36, v49
	v_cvt_pk_bf16_f32 v39, v36, s0
	v_add_f32_e32 v36, 1.0, v37
	s_mov_b32 s40, 0x2560c000
	v_rcp_f32_e32 v40, v36
	v_add_co_u32_e32 v36, vcc, s40, v66
	v_fmac_f32_e32 v59, v65, v49
	s_nop 0
	v_addc_co_u32_e32 v37, vcc, 0, v67, vcc
	global_store_short v[36:37], v39, off
	s_waitcnt vmcnt(29)
	v_lshlrev_b32_e32 v36, 16, v35
	v_mul_f32_e32 v35, 0xbfb8aa3b, v36
	v_exp_f32_e32 v35, v35
	v_mul_f32_e32 v34, v40, v34
	v_mul_f32_e32 v34, v34, v59
	s_mov_b32 s40, 0x25618000
	v_add_f32_e32 v35, 1.0, v35
	v_rcp_f32_e32 v39, v35
	v_cvt_pk_bf16_f32 v37, v34, s0
	v_add_co_u32_e32 v34, vcc, s40, v66
	v_fmac_f32_e32 v38, v80, v59
	s_nop 0
	v_addc_co_u32_e32 v35, vcc, 0, v67, vcc
	global_store_short v[34:35], v37, off
	v_mul_f32_e32 v34, v39, v36
	v_mul_f32_e32 v34, v34, v38
	v_cvt_pk_bf16_f32 v36, v34, s0
	s_mov_b64 s[100:101], 0x25624000
	v_lshl_add_u64 v[34:35], v[66:67], 0, s[100:101]
	global_store_short v[34:35], v36, off
	s_and_saveexec_b64 s[40:41], s[34:35]
	ds_write_b32 v149, v38 offset:55360
	s_or_b64 exec, exec, s[40:41]
	s_waitcnt vmcnt(22)
	v_lshlrev_b32_e32 v34, 16, v130
	v_and_b32_e32 v35, 0xffff0000, v130
	v_pk_fma_f32 v[34:35], v[104:105], v[34:35], v[100:101]
	s_waitcnt vmcnt(21)
	v_lshlrev_b32_e32 v36, 16, v132
	v_and_b32_e32 v37, 0xffff0000, v132
	v_pk_fma_f32 v[34:35], v[106:107], v[36:37], v[34:35]
	s_waitcnt vmcnt(20)
	v_lshlrev_b32_e32 v38, 16, v134
	v_and_b32_e32 v39, 0xffff0000, v134
	v_pk_fma_f32 v[34:35], v[108:109], v[38:39], v[34:35]
	s_waitcnt vmcnt(19)
	v_lshlrev_b32_e32 v40, 16, v169
	v_and_b32_e32 v41, 0xffff0000, v169
	v_pk_fma_f32 v[34:35], v[110:111], v[40:41], v[34:35]
	s_or_b32 s40, s93, 2
	v_cvt_pk_bf16_f32 v42, v34, v35
	v_pk_fma_f32 v[34:35], v[104:105], v[36:37], v[100:101]
	s_waitcnt vmcnt(18)
	v_lshlrev_b32_e32 v36, 16, v170
	v_pk_fma_f32 v[34:35], v[106:107], v[38:39], v[34:35]
	v_and_b32_e32 v37, 0xffff0000, v170
	v_pk_fma_f32 v[34:35], v[108:109], v[40:41], v[34:35]
	s_cmpk_gt_u32 s40, 0x7d
	v_pk_fma_f32 v[34:35], v[110:111], v[36:37], v[34:35]
	s_nop 0
	v_cvt_pk_bf16_f32 v34, v34, v35
	ds_write2_b32 v183, v42, v34 offset1:72
	v_pk_fma_f32 v[34:35], v[104:105], v[38:39], v[100:101]
	s_waitcnt vmcnt(17)
	v_lshlrev_b32_e32 v38, 16, v171
	v_pk_fma_f32 v[34:35], v[106:107], v[40:41], v[34:35]
	v_and_b32_e32 v39, 0xffff0000, v171
	v_pk_fma_f32 v[34:35], v[108:109], v[36:37], v[34:35]
	s_nop 0
	v_pk_fma_f32 v[34:35], v[110:111], v[38:39], v[34:35]
	s_nop 0
	v_cvt_pk_bf16_f32 v42, v34, v35
	v_pk_fma_f32 v[34:35], v[104:105], v[40:41], v[100:101]
	s_waitcnt vmcnt(16)
	v_lshlrev_b32_e32 v40, 16, v172
	v_pk_fma_f32 v[34:35], v[106:107], v[36:37], v[34:35]
	v_and_b32_e32 v41, 0xffff0000, v172
	v_pk_fma_f32 v[34:35], v[108:109], v[38:39], v[34:35]
	s_nop 0
	v_pk_fma_f32 v[34:35], v[110:111], v[40:41], v[34:35]
	s_nop 0
	v_cvt_pk_bf16_f32 v34, v34, v35
	ds_write2_b32 v183, v42, v34 offset0:144 offset1:216
	v_pk_fma_f32 v[34:35], v[104:105], v[36:37], v[100:101]
	s_waitcnt vmcnt(15)
	v_lshlrev_b32_e32 v36, 16, v173
	v_pk_fma_f32 v[34:35], v[106:107], v[38:39], v[34:35]
	v_and_b32_e32 v37, 0xffff0000, v173
	v_pk_fma_f32 v[34:35], v[108:109], v[40:41], v[34:35]
	s_nop 0
	v_pk_fma_f32 v[34:35], v[110:111], v[36:37], v[34:35]
	s_nop 0
	v_cvt_pk_bf16_f32 v42, v34, v35
	v_pk_fma_f32 v[34:35], v[104:105], v[38:39], v[100:101]
	s_waitcnt vmcnt(14)
	v_lshlrev_b32_e32 v38, 16, v174
	v_pk_fma_f32 v[34:35], v[106:107], v[40:41], v[34:35]
	v_and_b32_e32 v39, 0xffff0000, v174
	v_pk_fma_f32 v[34:35], v[108:109], v[36:37], v[34:35]
	s_nop 0
	v_pk_fma_f32 v[34:35], v[110:111], v[38:39], v[34:35]
	s_nop 0
	v_cvt_pk_bf16_f32 v34, v34, v35
	ds_write2_b32 v182, v42, v34 offset0:32 offset1:104
	v_pk_fma_f32 v[34:35], v[104:105], v[40:41], v[100:101]
	s_waitcnt vmcnt(13)
	v_lshlrev_b32_e32 v40, 16, v175
	v_pk_fma_f32 v[34:35], v[106:107], v[36:37], v[34:35]
	v_and_b32_e32 v41, 0xffff0000, v175
	v_pk_fma_f32 v[34:35], v[108:109], v[38:39], v[34:35]
	s_nop 0
	v_pk_fma_f32 v[34:35], v[110:111], v[40:41], v[34:35]
	s_nop 0
	v_cvt_pk_bf16_f32 v42, v34, v35
	v_pk_fma_f32 v[34:35], v[104:105], v[36:37], v[100:101]
	s_waitcnt vmcnt(12)
	v_lshlrev_b32_e32 v36, 16, v176
	v_pk_fma_f32 v[34:35], v[106:107], v[38:39], v[34:35]
	v_and_b32_e32 v37, 0xffff0000, v176
	v_pk_fma_f32 v[34:35], v[108:109], v[40:41], v[34:35]
	s_nop 0
	v_pk_fma_f32 v[34:35], v[110:111], v[36:37], v[34:35]
	s_nop 0
	v_cvt_pk_bf16_f32 v34, v34, v35
	ds_write2_b32 v182, v42, v34 offset0:176 offset1:248
	s_cbranch_scc1 .LBB0_281
	s_mov_b64 s[100:101], 0x25ee4000
	v_lshl_add_u64 v[34:35], v[50:51], 0, s[100:101]
	global_load_dword v130, v[34:35], off
	s_mov_b64 s[100:101], 0x25ef0000
	v_lshl_add_u64 v[34:35], v[50:51], 0, s[100:101]
	global_load_dword v132, v[34:35], off
	s_mov_b64 s[100:101], 0x25efc000
	v_lshl_add_u64 v[34:35], v[50:51], 0, s[100:101]
	global_load_dword v134, v[34:35], off
	s_mov_b64 s[100:101], 0x25f08000
	v_lshl_add_u64 v[34:35], v[50:51], 0, s[100:101]
	global_load_dword v169, v[34:35], off
	s_mov_b64 s[100:101], 0x25f14000
	v_lshl_add_u64 v[34:35], v[50:51], 0, s[100:101]
	global_load_dword v170, v[34:35], off
	s_mov_b64 s[100:101], 0x25f20000
	v_lshl_add_u64 v[34:35], v[50:51], 0, s[100:101]
	global_load_dword v171, v[34:35], off
	s_mov_b64 s[100:101], 0x25f2c000
	v_lshl_add_u64 v[34:35], v[50:51], 0, s[100:101]
	global_load_dword v172, v[34:35], off
	s_mov_b64 s[100:101], 0x25f38000
	v_lshl_add_u64 v[34:35], v[50:51], 0, s[100:101]
	global_load_dword v173, v[34:35], off
	s_mov_b64 s[100:101], 0x25f44000
	v_lshl_add_u64 v[34:35], v[50:51], 0, s[100:101]
	global_load_dword v174, v[34:35], off
	s_mov_b64 s[100:101], 0x25f50000
	v_lshl_add_u64 v[34:35], v[50:51], 0, s[100:101]
	global_load_dword v175, v[34:35], off
	s_mov_b64 s[100:101], 0x25f5c000
	v_lshl_add_u64 v[34:35], v[50:51], 0, s[100:101]
	global_load_dword v176, v[34:35], off

; #define LAS __attribute__((address_space(3)))
; DI float bf2f(unsigned h) { return __uint_as_float(h << 16); }
; DI float fexp2(float x) { return __builtin_amdgcn_exp2f(x); }
; DI float fsigmoid(float x) { return frcp(1.0f + fexp2(-LOG2E * x)); }
; DI void cv_issue_q(const CvJob& j, int idx, int lane, f32x4 (&v)[4], int r0) {
;     const float* W; int K, N, item; bf16* WT; const float* ks; cv_decode(j, idx, W, K, N, WT, ks, item);
;     const int nblk = N / 64, kb = item / nblk, nb = item % nblk, k0 = 64 * kb, n0 = 64 * nb, q = lane >> 4, c16 = lane & 15;
;     const char* ub = (const char*)(W + (size_t)(k0 + r0) * N + n0);
;     const unsigned vo = (unsigned)((16 * q) * N + 4 * c16) * 4u;
; #pragma unroll
;     for (int i = 0; i < 4; ++i) v[i] = *(const f32x4*)(ub + (size_t)i * N * 4 + vo);
; }
; DI void rglru_scan_unit(Frame& F, const Mix0Args& a, int u) {
;     ...
;         { bf16x8 xf[4], waf[4], wxf[4]; unsigned xcr[4];
; #pragma unroll
;           for (int ks = 0; ks < 4; ++ks) { xf[ks] = *(const LAS bf16x8*)(XCc + (l0_ + fr) * S128 + ks * 64 + fq * 16);
;               waf[ks] = *(const LAS bf16x8*)(WAT + (16 * jtile + fr) * S128 + ks * 64 + fq * 16); wxf[ks] = *(const LAS bf16x8*)(WXT + (16 * jtile + fr) * S128 + ks * 64 + fq * 16); }
; #pragma unroll
;           for (int r = 0; r < 4; ++r) xcr[r] = *(const LAS unsigned short*)(XCc + (l0_ + 4 * fq + r) * S128 + (qq * 32 + jj) * 2);
;           f32x4 R = zero4, I = zero4;
; #pragma unroll
;           for (int ks = 0; ks < 4; ++ks) { R = __builtin_amdgcn_mfma_f32_16x16x32_bf16(xf[ks], waf[ks], R, 0, 0, 0); I = __builtin_amdgcn_mfma_f32_16x16x32_bf16(xf[ks], wxf[ks], I, 0, 0, 0); }
; #pragma unroll
;           for (int r = 0; r < 4; ++r) {
;               const float rr = fsigmoid(R[r] + bav), ig = fsigmoid(I[r] + bxv);
;               const float aa = fexp2(-sp8l2 * rr); const float om = __builtin_fmaf(-aa, aa, 1.0f);
;               av[r] = aa; uv[r] = __builtin_sqrtf(om) * (ig * bf2f(xcr[r]));
;               Hseg = aa * Hseg + uv[r]; Aseg *= aa; } }
;         const int sgi = ltile * 4 + fq;
;         SEGA[jj * 20 + sgi] = Aseg; SEGH[jj * 20 + sgi] = Hseg;
.LBB0_287:
	s_lshr_b32 s79, s78, 6
	v_cvt_f32_u32_e32 v34, s79
	s_sub_i32 s90, 0, s79
	s_abs_i32 s89, s84
	s_ashr_i32 s88, s84, 31
	v_rcp_iflag_f32_e32 v34, v34
	v_mul_u32_u24_e32 v63, s78, v102
	v_or_b32_e32 v63, v63, v125
	v_lshlrev_b32_e32 v82, 2, v63
	v_mul_f32_e32 v34, 0x4f7ffffe, v34
	v_cvt_u32_f32_e32 v34, v34
	s_waitcnt vmcnt(15)
	v_lshlrev_b32_e32 v58, 16, v58
	s_waitcnt vmcnt(14)
	v_lshlrev_b32_e32 v56, 16, v56
	s_waitcnt vmcnt(13)
	v_lshlrev_b32_e32 v55, 16, v55
	v_readfirstlane_b32 s91, v34
	ds_read_b128 v[34:37], v164
	ds_read_b128 v[38:41], v103 offset:36864
	s_mul_i32 s90, s90, s91
	s_mul_hi_u32 s90, s91, s90
	s_add_i32 s91, s91, s90
	s_mul_hi_u32 s90, s89, s91
	s_mul_i32 s91, s90, s79
	s_sub_i32 s89, s89, s91
	s_add_i32 vcc_lo, s90, 1
	s_sub_i32 s91, s89, s79
	s_cmp_ge_u32 s89, s79
	ds_read_b128 v[42:45], v103 offset:46080
	ds_read_b128 v[46:49], v164 offset:64
	ds_read_b128 v[68:71], v103 offset:36928
	ds_read_b128 v[72:75], v103 offset:46144
	ds_read_b128 v[76:79], v164 offset:128
	s_cselect_b32 s90, vcc_lo, s90
	s_waitcnt lgkmcnt(5)
	v_mfma_f32_16x16x32_bf16 v[38:41], v[34:37], v[38:41], 0
	s_cselect_b32 s89, s91, s89
	s_add_i32 s91, s90, 1
	s_cmp_ge_u32 s89, s79
	s_cselect_b32 s89, s91, s90
	s_waitcnt lgkmcnt(4)
	v_mfma_f32_16x16x32_bf16 v[34:37], v[34:37], v[42:45], 0
	s_xor_b32 s89, s89, s88
	s_sub_i32 s88, s89, s88
	s_mul_i32 s79, s88, s79
	s_waitcnt lgkmcnt(2)
	v_mfma_f32_16x16x32_bf16 v[38:41], v[46:49], v[68:71], v[38:41]
	ds_read_b128 v[42:45], v103 offset:36992
	ds_read_b128 v[68:71], v164 offset:192
	s_lshl_b32 s88, s88, 6
	s_sub_i32 s79, s84, s79
	s_or_b32 s84, s88, 8
	s_waitcnt lgkmcnt(3)
	v_mfma_f32_16x16x32_bf16 v[34:37], v[46:49], v[72:75], v[34:37]
	ds_read_b128 v[46:49], v103 offset:37056
	s_mul_hi_i32 s91, s84, s78
	s_mul_i32 s90, s84, s78
	s_waitcnt lgkmcnt(2)
	v_mfma_f32_16x16x32_bf16 v[72:75], v[76:79], v[42:45], v[38:41]
	s_lshl_b32 s88, s79, 6
	s_lshl_b64 s[90:91], s[90:91], 2
	s_add_u32 s79, s40, s90
	s_addc_u32 s84, s41, s91
	s_ashr_i32 s89, s88, 31
	s_lshl_b64 s[40:41], s[88:89], 2
	s_waitcnt lgkmcnt(0)
	v_mfma_f32_16x16x32_bf16 v[72:75], v[68:71], v[46:49], v[72:75]
	s_add_u32 s40, s79, s40
	s_addc_u32 s41, s84, s41
	s_lshl_b32 s96, s78, 2
	v_lshl_add_u64 v[64:65], s[40:41], 0, v[82:83]
	v_lshl_add_u64 v[64:65], v[64:65], 0, s[96:97]
	s_nop 2
	v_add_f32_e32 v46, v165, v72
	v_lshl_add_u64 v[80:81], v[64:65], 0, s[96:97]
	global_load_dwordx4 v[38:41], v[64:65], off
	global_load_dwordx4 v[42:45], v[80:81], off
	ds_read_b128 v[178:181], v103 offset:46208
	ds_read_b128 v[182:185], v103 offset:46272
	v_mul_f32_e32 v46, 0xbfb8aa3b, v46
	v_exp_f32_e32 v48, v46
	s_waitcnt lgkmcnt(1)
	v_mfma_f32_16x16x32_bf16 v[76:79], v[76:79], v[178:181], v[34:37]
	v_lshl_add_u64 v[46:47], v[80:81], 0, s[96:97]
	v_add_f32_e32 v73, v165, v73
	s_nop 0
	v_add_f32_e32 v34, 1.0, v48
	v_rcp_f32_e32 v63, v34
	s_waitcnt lgkmcnt(0)
	v_mfma_f32_16x16x32_bf16 v[68:71], v[68:71], v[182:185], v[76:79]
	global_load_dwordx4 v[34:37], v82, s[40:41]
	s_nop 0
	global_load_dwordx4 v[46:49], v[46:47], off
	v_mul_f32_e32 v73, 0xbfb8aa3b, v73
	v_mul_f32_e64 v63, v63, -v168
	v_exp_f32_e32 v64, v63
	s_nop 1
	v_add_f32_e32 v63, v167, v68
	v_mul_f32_e32 v63, 0xbfb8aa3b, v63
	v_exp_f32_e32 v63, v63
	v_fma_f32 v65, -v64, v64, 1.0
	s_nop 0
	s_nop 0
	v_exp_f32_e32 v73, v73
	v_add_f32_e32 v63, 1.0, v63
	s_nop 0
	v_sqrt_f32_e32 v68, v65
	v_rcp_f32_e32 v63, v63
	ds_read_u16 v72, v113
	ds_read_u16 v76, v113 offset:288
	ds_read_u16 v77, v113 offset:576
	ds_read_u16 v78, v113 offset:864
	v_add_u32_e32 v79, -1, v68
	v_fma_f32 v80, -v79, v68, v65
	v_cmp_ge_f32_e64 s[40:41], 0, v80
	v_add_u32_e32 v80, 1, v68
	s_waitcnt lgkmcnt(3)
	v_lshlrev_b32_e32 v72, 16, v72
	v_cndmask_b32_e64 v79, v68, v79, s[40:41]
	v_fma_f32 v68, -v80, v68, v65
	v_cmp_lt_f32_e64 s[40:41], 0, v68
	v_mul_f32_e32 v63, v63, v72
	s_nop 0
	v_cndmask_b32_e64 v68, v79, v80, s[40:41]
	s_nop 0
	s_nop 0
	s_nop 0
	s_nop 1
	v_mov_b32_e32 v65, v68
	v_add_f32_e32 v68, 1.0, v73
	v_rcp_f32_e32 v68, v68
	v_mul_f32_e32 v80, v63, v65
	v_mul_f32_e64 v63, v68, -v168
	v_exp_f32_e32 v81, v63
	v_add_f32_e32 v63, v167, v69
	v_mul_f32_e32 v63, 0xbfb8aa3b, v63
	v_exp_f32_e32 v63, v63
	v_fma_f32 v65, -v81, v81, 1.0
	s_nop 0
	s_nop 0
	v_add_f32_e32 v63, 1.0, v63
	v_rcp_f32_e32 v63, v63
	s_nop 0
	v_sqrt_f32_e32 v68, v65
	v_fma_f32 v69, 0, v64, v80
	v_add_u32_e32 v72, -1, v68
	v_fma_f32 v73, -v72, v68, v65
	v_cmp_ge_f32_e64 s[40:41], 0, v73
	v_add_u32_e32 v73, 1, v68
	s_nop 0
	v_cndmask_b32_e64 v72, v68, v72, s[40:41]
	v_fma_f32 v68, -v73, v68, v65
	v_cmp_lt_f32_e64 s[40:41], 0, v68
	s_nop 1
	v_cndmask_b32_e64 v68, v72, v73, s[40:41]
	s_nop 0
	s_nop 0
	v_add_f32_e32 v72, v165, v74
	v_mul_f32_e32 v72, 0xbfb8aa3b, v72
	v_exp_f32_e32 v72, v72
	s_nop 0
	v_add_f32_e32 v72, 1.0, v72
	v_rcp_f32_e32 v72, v72
	v_mov_b32_e32 v65, v68
	s_waitcnt lgkmcnt(2)
	v_lshlrev_b32_e32 v68, 16, v76
	v_mul_f32_e32 v63, v63, v68
	v_mul_f32_e32 v82, v63, v65
	v_mul_f32_e64 v65, v72, -v168
	v_exp_f32_e32 v122, v65
	v_fma_f32 v63, v81, v69, v82
	v_add_f32_e32 v65, v167, v70
	v_mul_f32_e32 v65, 0xbfb8aa3b, v65
	v_fma_f32 v68, -v122, v122, 1.0
	s_nop 0
	s_nop 0
	v_exp_f32_e32 v65, v65
	v_mul_f32_e32 v70, v64, v81
	s_nop 0
	v_sqrt_f32_e32 v69, v68
	v_add_f32_e32 v65, 1.0, v65
	v_rcp_f32_e32 v65, v65
	v_mul_f32_e32 v70, v122, v70
	v_add_u32_e32 v72, -1, v69
	v_fma_f32 v73, -v72, v69, v68
	v_cmp_ge_f32_e64 s[40:41], 0, v73
	v_add_u32_e32 v73, 1, v69
	s_nop 0
	v_cndmask_b32_e64 v72, v69, v72, s[40:41]
	v_fma_f32 v69, -v73, v69, v68
	v_cmp_lt_f32_e64 s[40:41], 0, v69
	s_nop 1
	v_cndmask_b32_e64 v69, v72, v73, s[40:41]
	s_nop 0
	s_nop 0
	v_add_f32_e32 v72, v165, v75
	v_mul_f32_e32 v72, 0xbfb8aa3b, v72
	v_exp_f32_e32 v72, v72
	s_nop 0
	v_add_f32_e32 v72, 1.0, v72
	v_rcp_f32_e32 v72, v72
	v_mov_b32_e32 v68, v69
	s_waitcnt lgkmcnt(1)
	v_lshlrev_b32_e32 v69, 16, v77
	v_mul_f32_e32 v65, v65, v69
	v_mul_f32_e32 v124, v65, v68
	v_fma_f32 v65, v122, v63, v124
	v_mul_f32_e64 v63, v72, -v168
	v_exp_f32_e32 v126, v63
	v_add_f32_e32 v63, v167, v71
	v_mul_f32_e32 v63, 0xbfb8aa3b, v63
	v_exp_f32_e32 v63, v63
	v_fma_f32 v68, -v126, v126, 1.0
	s_nop 0
	s_nop 0
	v_add_f32_e32 v63, 1.0, v63
	v_rcp_f32_e32 v63, v63
	s_nop 0
	v_sqrt_f32_e32 v69, v68
	s_nop 0
	v_add_u32_e32 v71, -1, v69
	v_fma_f32 v72, -v71, v69, v68
	v_cmp_ge_f32_e64 s[40:41], 0, v72
	v_add_u32_e32 v72, 1, v69
	s_nop 0
	v_cndmask_b32_e64 v71, v69, v71, s[40:41]
	v_fma_f32 v69, -v72, v69, v68
	v_cmp_lt_f32_e64 s[40:41], 0, v69
	s_nop 1
	v_cndmask_b32_e64 v69, v71, v72, s[40:41]
	s_nop 0
	s_nop 0
	s_nop 0
	s_mov_b32 s40, 0x25900000
	s_nop 0
	v_mov_b32_e32 v68, v69
	s_waitcnt lgkmcnt(0)
	v_lshlrev_b32_e32 v69, 16, v78
	v_mul_f32_e32 v63, v63, v69
	v_mul_f32_e32 v63, v63, v68
	v_fma_f32 v65, v126, v65, v63
	v_mul_f32_e32 v68, v126, v70
	ds_write2st64_b32 v150, v68, v65 offset0:216 offset1:226
	s_waitcnt lgkmcnt(0)
	s_barrier
; #define LAS __attribute__((address_space(3)))
; DI float bf2f(unsigned h) { return __uint_as_float(h << 16); }
; DI unsigned pk2(float lo, float hi) { f32x2 v = {lo, hi}; bf16v2 b = __builtin_convertvector(v, bf16v2); return __builtin_bit_cast(unsigned, b); }
; DI float fsilu(float x) { return x * fsigmoid(x); }
; DI void rglru_scan_unit(Frame& F, const Mix0Args& a, int u) {
;     ...
;         float carry = HPREV[jj * 20 + (n & 1)]; float sa[15], sh[15];
;         { f32x4 a4[4], h4[4];
; #pragma unroll
;           for (int i = 0; i < 4; ++i) { a4[i] = *(const LAS f32x4*)(SEGA + jj * 20 + 4 * i); h4[i] = *(const LAS f32x4*)(SEGH + jj * 20 + 4 * i); }
; #pragma unroll
;           for (int s = 0; s < 15; ++s) { sa[s] = a4[s >> 2][s & 3]; sh[s] = h4[s >> 2][s & 3]; } }
; #pragma unroll
;         for (int s = 0; s < 15; ++s) carry = (s < sgi) ? sa[s] * carry + sh[s] : carry;
; #pragma unroll
;         for (int r = 0; r < 4; ++r) { carry = av[r] * carry + uv[r];
;             const float o = carry * fsilu(bf2f(gb_cur[r]));
;             obcol[(row0 + l0_ + 4 * fq + r) * a.out_ld] = (bf16)(pk2(o, 0.f) & 0xffffu); }
;         if (sgi == 15) HPREV[jj * 20 + ((n + 1) & 1)] = carry;
	ds_read_b32 v65, v149 offset:55360
	ds_read_b128 v[68:71], v149 offset:57856
	ds_read_b128 v[72:75], v149 offset:57872
	ds_read_b128 v[76:79], v149 offset:57888
	ds_read_b128 v[178:181], v149 offset:55296
	ds_read_b128 v[182:185], v149 offset:55312
	ds_read_b128 v[186:189], v149 offset:55328
	ds_read_b128 v[190:193], v149 offset:55344
	ds_read_b128 v[194:197], v149 offset:57904
	s_waitcnt lgkmcnt(4)
	v_fma_f32 v68, v65, v178, v68
	v_cndmask_b32_e64 v65, v68, v65, s[10:11]
	v_fma_f32 v68, v179, v65, v69
	v_cndmask_b32_e64 v65, v65, v68, s[12:13]
	v_fma_f32 v68, v180, v65, v70
	v_cndmask_b32_e64 v65, v65, v68, s[14:15]
	v_fmac_f32_e32 v71, v181, v65
	v_cndmask_b32_e64 v65, v71, v65, s[0:1]
	s_waitcnt lgkmcnt(3)
	v_fma_f32 v68, v182, v65, v72
	v_cndmask_b32_e64 v65, v65, v68, s[16:17]
	v_fma_f32 v68, v183, v65, v73
	v_cndmask_b32_e64 v65, v65, v68, s[18:19]
	v_fma_f32 v68, v184, v65, v74
	v_cndmask_b32_e64 v65, v65, v68, s[20:21]
	v_fmac_f32_e32 v75, v185, v65
	v_cndmask_b32_e64 v65, v65, v75, s[38:39]
	s_waitcnt lgkmcnt(2)
	v_fma_f32 v68, v186, v65, v76
	v_cndmask_b32_e64 v65, v65, v68, s[22:23]
	v_fma_f32 v68, v187, v65, v77
	v_cndmask_b32_e64 v65, v65, v68, s[24:25]
	v_fma_f32 v68, v188, v65, v78
	v_cndmask_b32_e64 v65, v65, v68, s[26:27]
	v_fmac_f32_e32 v79, v189, v65
	v_mul_f32_e32 v69, 0xbfb8aa3b, v58
	v_cndmask_b32_e64 v65, v65, v79, s[4:5]
	v_exp_f32_e32 v69, v69
	s_waitcnt lgkmcnt(0)
	v_fma_f32 v68, v190, v65, v194
	v_cndmask_b32_e64 v65, v65, v68, s[28:29]
	v_fma_f32 v68, v191, v65, v195
	v_cndmask_b32_e64 v65, v65, v68, s[30:31]
	v_add_f32_e32 v68, 1.0, v69
	v_rcp_f32_e32 v68, v68
	v_fmac_f32_e32 v196, v192, v65
	v_cndmask_b32_e64 v65, v65, v196, s[34:35]
	v_fmac_f32_e32 v80, v64, v65
	v_mul_f32_e32 v64, 0xbfb8aa3b, v56
	v_mul_f32_e32 v58, v68, v58
	v_exp_f32_e32 v68, v64
	v_mul_f32_e32 v58, v58, v80
	v_add_co_u32_e32 v64, vcc, s40, v66
	v_cvt_pk_bf16_f32 v58, v58, s0
	s_nop 0
	v_addc_co_u32_e32 v65, vcc, 0, v67, vcc
	global_store_short v[64:65], v58, off
	v_add_f32_e32 v58, 1.0, v68
	v_mul_f32_e32 v64, 0xbfb8aa3b, v55
	v_rcp_f32_e32 v58, v58
	v_exp_f32_e32 v64, v64
	v_fmac_f32_e32 v82, v81, v80
	s_mov_b32 s40, 0x2590c000
	v_mul_f32_e32 v56, v58, v56
	v_add_f32_e32 v58, 1.0, v64
	v_rcp_f32_e32 v58, v58
	v_mul_f32_e32 v56, v56, v82
	v_add_co_u32_e32 v64, vcc, s40, v66
	v_cvt_pk_bf16_f32 v56, v56, s0
	s_nop 0
	v_addc_co_u32_e32 v65, vcc, 0, v67, vcc
	v_mul_f32_e32 v55, v58, v55
	s_waitcnt vmcnt(17)
	v_lshlrev_b32_e32 v58, 16, v57
	global_store_short v[64:65], v56, off
	v_mul_f32_e32 v56, 0xbfb8aa3b, v58
	v_exp_f32_e32 v57, v56
	v_fmac_f32_e32 v124, v122, v82
	s_mov_b32 s40, 0x25918000
	v_mul_f32_e32 v55, v55, v124
	v_add_f32_e32 v57, 1.0, v57
	v_rcp_f32_e32 v64, v57
	v_add_co_u32_e32 v56, vcc, s40, v66
	v_cvt_pk_bf16_f32 v55, v55, s0
	s_nop 0
	v_addc_co_u32_e32 v57, vcc, 0, v67, vcc
	global_store_short v[56:57], v55, off
	v_fmac_f32_e32 v63, v126, v124
	v_mul_f32_e32 v55, v64, v58
	v_mul_f32_e32 v55, v55, v63
	s_mov_b64 s[100:101], 0x25924000
	v_lshl_add_u64 v[56:57], v[66:67], 0, s[100:101]
	v_cvt_pk_bf16_f32 v55, v55, s0
	global_store_short v[56:57], v55, off
	s_and_saveexec_b64 s[40:41], s[34:35]
	ds_write_b32 v149, v63 offset:55364
	s_or_b64 exec, exec, s[40:41]
	s_or_b32 s78, s93, 3
	s_cmpk_lt_u32 s78, 0x7f
	s_cselect_b64 s[40:41], -1, 0
	s_cmpk_gt_u32 s78, 0x7e
	s_cbranch_scc1 .LBB0_291
	v_lshlrev_b32_e32 v56, 16, v130
	v_and_b32_e32 v57, 0xffff0000, v130
	v_pk_fma_f32 v[56:57], v[104:105], v[56:57], v[100:101]
	v_lshlrev_b32_e32 v64, 16, v132
	v_and_b32_e32 v65, 0xffff0000, v132
	v_pk_fma_f32 v[56:57], v[106:107], v[64:65], v[56:57]
	v_lshlrev_b32_e32 v68, 16, v134
	v_and_b32_e32 v69, 0xffff0000, v134
	v_pk_fma_f32 v[56:57], v[108:109], v[68:69], v[56:57]
	s_waitcnt vmcnt(19)
	v_lshlrev_b32_e32 v70, 16, v169
	v_and_b32_e32 v71, 0xffff0000, v169
	v_pk_fma_f32 v[56:57], v[110:111], v[70:71], v[56:57]
	s_nop 0
	v_cvt_pk_bf16_f32 v55, v56, v57
	v_pk_fma_f32 v[56:57], v[104:105], v[64:65], v[100:101]
	s_waitcnt vmcnt(18)
	v_lshlrev_b32_e32 v64, 16, v170
	v_pk_fma_f32 v[56:57], v[106:107], v[68:69], v[56:57]
	v_and_b32_e32 v65, 0xffff0000, v170
	v_pk_fma_f32 v[56:57], v[108:109], v[70:71], v[56:57]
	s_nop 0
	v_pk_fma_f32 v[56:57], v[110:111], v[64:65], v[56:57]
	s_nop 0
	v_cvt_pk_bf16_f32 v56, v56, v57
	ds_write2_b32 v123, v55, v56 offset1:72
	v_pk_fma_f32 v[56:57], v[104:105], v[68:69], v[100:101]
	s_waitcnt vmcnt(17)
	v_lshlrev_b32_e32 v68, 16, v171
	v_pk_fma_f32 v[56:57], v[106:107], v[70:71], v[56:57]
	v_and_b32_e32 v69, 0xffff0000, v171
	v_pk_fma_f32 v[56:57], v[108:109], v[64:65], v[56:57]
	s_nop 0
	v_pk_fma_f32 v[56:57], v[110:111], v[68:69], v[56:57]
	s_nop 0
	v_cvt_pk_bf16_f32 v55, v56, v57
	v_pk_fma_f32 v[56:57], v[104:105], v[70:71], v[100:101]
	s_waitcnt vmcnt(16)
	v_lshlrev_b32_e32 v70, 16, v172
	v_pk_fma_f32 v[56:57], v[106:107], v[64:65], v[56:57]
	v_and_b32_e32 v71, 0xffff0000, v172
	v_pk_fma_f32 v[56:57], v[108:109], v[68:69], v[56:57]
	s_nop 0
	v_pk_fma_f32 v[56:57], v[110:111], v[70:71], v[56:57]
	s_nop 0
	v_cvt_pk_bf16_f32 v56, v56, v57
	ds_write2_b32 v123, v55, v56 offset0:144 offset1:216
	v_pk_fma_f32 v[56:57], v[104:105], v[64:65], v[100:101]
	s_waitcnt vmcnt(15)
	v_lshlrev_b32_e32 v64, 16, v173
	v_pk_fma_f32 v[56:57], v[106:107], v[68:69], v[56:57]
	v_and_b32_e32 v65, 0xffff0000, v173
	v_pk_fma_f32 v[56:57], v[108:109], v[70:71], v[56:57]
	s_nop 0
	v_pk_fma_f32 v[56:57], v[110:111], v[64:65], v[56:57]
	s_nop 0
	v_cvt_pk_bf16_f32 v55, v56, v57
	v_pk_fma_f32 v[56:57], v[104:105], v[68:69], v[100:101]
	s_waitcnt vmcnt(14)
	v_lshlrev_b32_e32 v68, 16, v174
	v_pk_fma_f32 v[56:57], v[106:107], v[70:71], v[56:57]
	v_and_b32_e32 v69, 0xffff0000, v174
	v_pk_fma_f32 v[56:57], v[108:109], v[64:65], v[56:57]
	s_nop 0
	v_pk_fma_f32 v[56:57], v[110:111], v[68:69], v[56:57]
	s_nop 0
	v_cvt_pk_bf16_f32 v56, v56, v57
	ds_write2_b32 v54, v55, v56 offset0:32 offset1:104
	v_pk_fma_f32 v[56:57], v[104:105], v[70:71], v[100:101]
	s_waitcnt vmcnt(13)
	v_lshlrev_b32_e32 v70, 16, v175
	v_pk_fma_f32 v[56:57], v[106:107], v[64:65], v[56:57]
	v_and_b32_e32 v71, 0xffff0000, v175
	v_pk_fma_f32 v[56:57], v[108:109], v[68:69], v[56:57]
	s_nop 0
	v_pk_fma_f32 v[56:57], v[110:111], v[70:71], v[56:57]
	s_nop 0
	v_cvt_pk_bf16_f32 v55, v56, v57
	v_pk_fma_f32 v[56:57], v[104:105], v[64:65], v[100:101]
	s_waitcnt vmcnt(12)
	v_lshlrev_b32_e32 v64, 16, v176
	v_pk_fma_f32 v[56:57], v[106:107], v[68:69], v[56:57]
	v_and_b32_e32 v65, 0xffff0000, v176
	v_pk_fma_f32 v[56:57], v[108:109], v[70:71], v[56:57]
	s_nop 0
	v_pk_fma_f32 v[56:57], v[110:111], v[64:65], v[56:57]
	s_nop 0
	v_cvt_pk_bf16_f32 v56, v56, v57
	ds_write2_b32 v54, v55, v56 offset0:176 offset1:248

; #define LAS __attribute__((address_space(3)))
; DI float bf2f(unsigned h) { return __uint_as_float(h << 16); }
; DI float fexp2(float x) { return __builtin_amdgcn_exp2f(x); }
; DI float fsigmoid(float x) { return frcp(1.0f + fexp2(-LOG2E * x)); }
; DI void cv_issue_q(const CvJob& j, int idx, int lane, f32x4 (&v)[4], int r0) {
;     const float* W; int K, N, item; bf16* WT; const float* ks; cv_decode(j, idx, W, K, N, WT, ks, item);
;     const int nblk = N / 64, kb = item / nblk, nb = item % nblk, k0 = 64 * kb, n0 = 64 * nb, q = lane >> 4, c16 = lane & 15;
;     const char* ub = (const char*)(W + (size_t)(k0 + r0) * N + n0);
;     const unsigned vo = (unsigned)((16 * q) * N + 4 * c16) * 4u;
; #pragma unroll
;     for (int i = 0; i < 4; ++i) v[i] = *(const f32x4*)(ub + (size_t)i * N * 4 + vo);
; }
; DI void rglru_scan_unit(Frame& F, const Mix0Args& a, int u) {
;     ...
;         { bf16x8 xf[4], waf[4], wxf[4]; unsigned xcr[4];
; #pragma unroll
;           for (int ks = 0; ks < 4; ++ks) { xf[ks] = *(const LAS bf16x8*)(XCc + (l0_ + fr) * S128 + ks * 64 + fq * 16);
;               waf[ks] = *(const LAS bf16x8*)(WAT + (16 * jtile + fr) * S128 + ks * 64 + fq * 16); wxf[ks] = *(const LAS bf16x8*)(WXT + (16 * jtile + fr) * S128 + ks * 64 + fq * 16); }
; #pragma unroll
;           for (int r = 0; r < 4; ++r) xcr[r] = *(const LAS unsigned short*)(XCc + (l0_ + 4 * fq + r) * S128 + (qq * 32 + jj) * 2);
;           f32x4 R = zero4, I = zero4;
; #pragma unroll
;           for (int ks = 0; ks < 4; ++ks) { R = __builtin_amdgcn_mfma_f32_16x16x32_bf16(xf[ks], waf[ks], R, 0, 0, 0); I = __builtin_amdgcn_mfma_f32_16x16x32_bf16(xf[ks], wxf[ks], I, 0, 0, 0); }
; #pragma unroll
;           for (int r = 0; r < 4; ++r) {
;               const float rr = fsigmoid(R[r] + bav), ig = fsigmoid(I[r] + bxv);
;               const float aa = fexp2(-sp8l2 * rr); const float om = __builtin_fmaf(-aa, aa, 1.0f);
;               av[r] = aa; uv[r] = __builtin_sqrtf(om) * (ig * bf2f(xcr[r]));
;               Hseg = aa * Hseg + uv[r]; Aseg *= aa; } }
;         const int sgi = ltile * 4 + fq;
;         SEGA[jj * 20 + sgi] = Aseg; SEGH[jj * 20 + sgi] = Hseg;
.LBB0_302:
	s_lshr_b32 s41, s40, 6
	v_cvt_f32_u32_e32 v50, s41
	s_sub_i32 s84, 0, s41
	s_abs_i32 s79, s87
	s_ashr_i32 s78, s87, 31
	v_rcp_iflag_f32_e32 v50, v50
	v_mul_u32_u24_e32 v76, s40, v102
	v_or_b32_e32 v80, v76, v125
	v_lshlrev_b32_e32 v82, 2, v80
	v_mul_f32_e32 v50, 0x4f7ffffe, v50
	v_cvt_u32_f32_e32 v50, v50
	v_lshlrev_b32_e32 v71, 16, v71
	v_lshlrev_b32_e32 v69, 16, v69
	ds_read_b128 v[54:57], v103 offset:36864
	v_readfirstlane_b32 s88, v50
	ds_read_b128 v[50:53], v164 offset:18432
	s_mul_i32 s84, s84, s88
	s_mul_hi_u32 s84, s88, s84
	s_add_i32 s88, s88, s84
	s_mul_hi_u32 s84, s79, s88
	s_mul_i32 s88, s84, s41
	s_sub_i32 s79, s79, s88
	s_add_i32 s89, s84, 1
	s_sub_i32 s88, s79, s41
	s_cmp_ge_u32 s79, s41
	ds_read_b128 v[58:61], v103 offset:46080
	ds_read_b128 v[62:65], v164 offset:18496
	ds_read_b128 v[72:75], v103 offset:36928
	ds_read_b128 v[76:79], v103 offset:46144
	ds_read_b128 v[182:185], v164 offset:18560
	s_cselect_b32 s84, s89, s84
	s_waitcnt lgkmcnt(5)
	v_mfma_f32_16x16x32_bf16 v[54:57], v[50:53], v[54:57], 0
	s_cselect_b32 s79, s88, s79
	s_add_i32 s88, s84, 1
	s_cmp_ge_u32 s79, s41
	s_cselect_b32 s79, s88, s84
	s_waitcnt lgkmcnt(4)
	v_mfma_f32_16x16x32_bf16 v[50:53], v[50:53], v[58:61], 0
	s_xor_b32 s79, s79, s78
	s_sub_i32 s78, s79, s78
	s_mul_i32 s41, s78, s41
	s_waitcnt lgkmcnt(2)
	v_mfma_f32_16x16x32_bf16 v[54:57], v[62:65], v[72:75], v[54:57]
	ds_read_b128 v[58:61], v103 offset:36992
	ds_read_b128 v[72:75], v164 offset:18624
	s_lshl_b32 s78, s78, 6
	s_or_b32 s79, s78, 12
	s_waitcnt lgkmcnt(3)
	v_mfma_f32_16x16x32_bf16 v[50:53], v[62:65], v[76:79], v[50:53]
	ds_read_b128 v[76:79], v103 offset:37056
	s_sub_i32 s41, s87, s41
	s_mul_hi_i32 s89, s79, s40
	s_mul_i32 s88, s79, s40
	s_waitcnt lgkmcnt(2)
	v_mfma_f32_16x16x32_bf16 v[54:57], v[182:185], v[58:61], v[54:57]
	s_lshl_b32 s78, s41, 6
	s_lshl_b64 s[88:89], s[88:89], 2
	s_add_u32 s41, s36, s88
	s_addc_u32 s84, s37, s89
	s_ashr_i32 s79, s78, 31
	s_lshl_b64 s[36:37], s[78:79], 2
	s_waitcnt lgkmcnt(0)
	v_mfma_f32_16x16x32_bf16 v[76:79], v[72:75], v[76:79], v[54:57]
	s_add_u32 s36, s41, s36
	s_addc_u32 s37, s84, s37
	s_lshl_b32 s96, s40, 2
	v_lshl_add_u64 v[80:81], s[36:37], 0, v[82:83]
	v_lshl_add_u64 v[62:63], v[80:81], 0, s[96:97]
	s_nop 2
	v_add_f32_e32 v54, v165, v76
	v_lshl_add_u64 v[80:81], v[62:63], 0, s[96:97]
	global_load_dwordx4 v[58:61], v[62:63], off
	s_nop 0
	global_load_dwordx4 v[62:65], v[80:81], off
	ds_read_b128 v[186:189], v103 offset:46208
	ds_read_b128 v[190:193], v103 offset:46272
	v_mul_f32_e32 v54, 0xbfb8aa3b, v54
	v_exp_f32_e32 v54, v54
	s_waitcnt lgkmcnt(1)
	v_mfma_f32_16x16x32_bf16 v[182:185], v[182:185], v[186:189], v[50:53]
	v_lshl_add_u64 v[80:81], v[80:81], 0, s[96:97]
	v_add_f32_e32 v77, v165, v77
	s_nop 0
	v_add_f32_e32 v50, 1.0, v54
	v_rcp_f32_e32 v76, v50
	global_load_dwordx4 v[54:57], v82, s[36:37]
	global_load_dwordx4 v[50:53], v[80:81], off
	s_waitcnt lgkmcnt(0)
	v_mfma_f32_16x16x32_bf16 v[72:75], v[72:75], v[190:193], v[182:185]
	v_mul_f32_e32 v77, 0xbfb8aa3b, v77
	v_mul_f32_e64 v76, v76, -v168
	v_exp_f32_e32 v82, v76
	v_exp_f32_e32 v77, v77
	ds_read_u16 v81, v177 offset:18432
	ds_read_u16 v122, v177 offset:18720
	ds_read_u16 v124, v177 offset:19008
	ds_read_u16 v126, v177 offset:19296
	v_add_f32_e32 v72, v167, v72
	v_fma_f32 v76, -v82, v82, 1.0
	s_nop 0
	s_nop 0
	v_mul_f32_e32 v72, 0xbfb8aa3b, v72
	v_exp_f32_e32 v72, v72
	s_nop 0
	v_sqrt_f32_e32 v80, v76
	v_add_f32_e32 v77, 1.0, v77
	v_add_f32_e32 v72, 1.0, v72
	v_rcp_f32_e32 v72, v72
	v_add_u32_e32 v128, -1, v80
	v_fma_f32 v182, -v128, v80, v76
	v_cmp_ge_f32_e64 s[36:37], 0, v182
	v_add_u32_e32 v182, 1, v80
	v_rcp_f32_e32 v77, v77
	v_cndmask_b32_e64 v128, v80, v128, s[36:37]
	v_fma_f32 v80, -v182, v80, v76
	v_cmp_lt_f32_e64 s[36:37], 0, v80
	v_add_f32_e32 v78, v165, v78
	v_mul_f32_e32 v78, 0xbfb8aa3b, v78
	v_cndmask_b32_e64 v80, v128, v182, s[36:37]
	s_nop 0
	s_nop 0
	s_nop 0
	v_exp_f32_e32 v78, v78
	v_add_f32_e32 v74, v167, v74
	v_mov_b32_e32 v76, v80
	s_waitcnt lgkmcnt(3)
	v_lshlrev_b32_e32 v80, 16, v81
	v_mul_f32_e32 v72, v72, v80
	v_mul_f32_e32 v128, v72, v76
	v_mul_f32_e64 v72, v77, -v168
	v_exp_f32_e32 v206, v72
	v_add_f32_e32 v72, v167, v73
	v_mul_f32_e32 v72, 0xbfb8aa3b, v72
	v_exp_f32_e32 v72, v72
	v_fma_f32 v73, -v206, v206, 1.0
	s_nop 0
	s_nop 0
	v_add_f32_e32 v72, 1.0, v72
	v_add_f32_e32 v78, 1.0, v78
	s_nop 0
	v_sqrt_f32_e32 v76, v73
	v_rcp_f32_e32 v72, v72
	v_rcp_f32_e32 v78, v78
	v_fma_f32 v77, 0, v82, v128
	v_add_u32_e32 v80, -1, v76
	v_fma_f32 v81, -v80, v76, v73
	v_cmp_ge_f32_e64 s[36:37], 0, v81
	v_add_u32_e32 v81, 1, v76
	v_mul_f32_e32 v74, 0xbfb8aa3b, v74
	v_cndmask_b32_e64 v80, v76, v80, s[36:37]
	v_fma_f32 v76, -v81, v76, v73
	v_cmp_lt_f32_e64 s[36:37], 0, v76
	v_exp_f32_e32 v74, v74
	v_add_f32_e32 v79, v165, v79
	v_cndmask_b32_e64 v76, v80, v81, s[36:37]
	s_nop 0
	s_nop 0
	s_nop 0
	v_mul_f32_e32 v79, 0xbfb8aa3b, v79
	v_exp_f32_e32 v79, v79
	v_mov_b32_e32 v73, v76
	s_waitcnt lgkmcnt(2)
	v_lshlrev_b32_e32 v76, 16, v122
	v_mul_f32_e32 v72, v72, v76
	v_mul_f32_e64 v76, v78, -v168
	v_exp_f32_e32 v122, v76
	v_mul_f32_e32 v73, v72, v73
	v_fma_f32 v72, v206, v77, v73
	v_add_f32_e32 v74, 1.0, v74
	v_fma_f32 v76, -v122, v122, 1.0
	s_nop 0
	s_nop 0
	v_rcp_f32_e32 v74, v74
	v_add_f32_e32 v79, 1.0, v79
	s_nop 0
	v_sqrt_f32_e32 v77, v76
	v_rcp_f32_e32 v79, v79
	v_mul_f32_e32 v78, v82, v206
	v_add_u32_e32 v80, -1, v77
	v_fma_f32 v81, -v80, v77, v76
	v_cmp_ge_f32_e64 s[36:37], 0, v81
	v_add_u32_e32 v81, 1, v77
	s_nop 0
	v_cndmask_b32_e64 v80, v77, v80, s[36:37]
	v_fma_f32 v77, -v81, v77, v76
	v_cmp_lt_f32_e64 s[36:37], 0, v77
	s_nop 1
	v_cndmask_b32_e64 v77, v80, v81, s[36:37]
	s_nop 0
	s_nop 0
	s_nop 0
	s_nop 1
	v_mov_b32_e32 v76, v77
	s_waitcnt lgkmcnt(1)
	v_lshlrev_b32_e32 v77, 16, v124
	v_mul_f32_e32 v74, v74, v77
	v_mul_f32_e32 v124, v74, v76
	v_fma_f32 v74, v122, v72, v124
	v_mul_f32_e64 v72, v79, -v168
	v_exp_f32_e32 v207, v72
	v_add_f32_e32 v72, v167, v75
	v_mul_f32_e32 v72, 0xbfb8aa3b, v72
	v_exp_f32_e32 v72, v72
	v_fma_f32 v75, -v207, v207, 1.0
	s_nop 0
	s_nop 0
	v_mul_f32_e32 v77, v122, v78
	v_add_f32_e32 v72, 1.0, v72
	s_nop 0
	v_sqrt_f32_e32 v76, v75
	v_rcp_f32_e32 v72, v72
	v_add_u32_e32 v78, -1, v76
	v_fma_f32 v79, -v78, v76, v75
	v_cmp_ge_f32_e64 s[36:37], 0, v79
	v_add_u32_e32 v79, 1, v76
	s_nop 0
	v_cndmask_b32_e64 v78, v76, v78, s[36:37]
	v_fma_f32 v76, -v79, v76, v75
	v_cmp_lt_f32_e64 s[36:37], 0, v76
	s_nop 1
	v_cndmask_b32_e64 v76, v78, v79, s[36:37]
	s_nop 0
	s_nop 0
	s_nop 0
	s_mov_b32 s36, 0x25c00000
	s_nop 0
	v_mov_b32_e32 v75, v76
	s_waitcnt lgkmcnt(0)
	v_lshlrev_b32_e32 v76, 16, v126
	v_mul_f32_e32 v72, v72, v76
	v_mul_f32_e32 v72, v72, v75
	v_fma_f32 v74, v207, v74, v72
	v_mul_f32_e32 v75, v207, v77
	ds_write2st64_b32 v150, v75, v74 offset0:236 offset1:246
	s_waitcnt lgkmcnt(0)
	s_barrier
; #define LAS __attribute__((address_space(3)))
; DI float bf2f(unsigned h) { return __uint_as_float(h << 16); }
; DI unsigned pk2(float lo, float hi) { f32x2 v = {lo, hi}; bf16v2 b = __builtin_convertvector(v, bf16v2); return __builtin_bit_cast(unsigned, b); }
; DI float fsilu(float x) { return x * fsigmoid(x); }
; DI void rglru_scan_unit(Frame& F, const Mix0Args& a, int u) {
;     ...
;         float carry = HPREV[jj * 20 + (n & 1)]; float sa[15], sh[15];
;         { f32x4 a4[4], h4[4];
; #pragma unroll
;           for (int i = 0; i < 4; ++i) { a4[i] = *(const LAS f32x4*)(SEGA + jj * 20 + 4 * i); h4[i] = *(const LAS f32x4*)(SEGH + jj * 20 + 4 * i); }
; #pragma unroll
;           for (int s = 0; s < 15; ++s) { sa[s] = a4[s >> 2][s & 3]; sh[s] = h4[s >> 2][s & 3]; } }
; #pragma unroll
;         for (int s = 0; s < 15; ++s) carry = (s < sgi) ? sa[s] * carry + sh[s] : carry;
; #pragma unroll
;         for (int r = 0; r < 4; ++r) { carry = av[r] * carry + uv[r];
;             const float o = carry * fsilu(bf2f(gb_cur[r]));
;             obcol[(row0 + l0_ + 4 * fq + r) * a.out_ld] = (bf16)(pk2(o, 0.f) & 0xffffu); }
;         if (sgi == 15) HPREV[jj * 20 + ((n + 1) & 1)] = carry;
	ds_read_b32 v126, v149 offset:55364
	ds_read_b128 v[74:77], v149 offset:60416
	ds_read_b128 v[78:81], v149 offset:62976
	ds_read_b128 v[182:185], v149 offset:60432
	ds_read_b128 v[186:189], v149 offset:60448
	ds_read_b128 v[190:193], v149 offset:62992
	ds_read_b128 v[194:197], v149 offset:63008
	ds_read_b128 v[198:201], v149 offset:60464
	ds_read_b128 v[202:205], v149 offset:63024
	s_waitcnt lgkmcnt(6)
	v_fma_f32 v74, v126, v74, v78
	v_cndmask_b32_e64 v74, v74, v126, s[10:11]
	v_fma_f32 v75, v75, v74, v79
	v_cndmask_b32_e64 v74, v74, v75, s[12:13]
	v_fma_f32 v75, v76, v74, v80
	v_cndmask_b32_e64 v74, v74, v75, s[14:15]
	v_fmac_f32_e32 v81, v77, v74
	v_cndmask_b32_e64 v74, v81, v74, s[0:1]
	s_waitcnt lgkmcnt(3)
	v_fma_f32 v75, v182, v74, v190
	v_cndmask_b32_e64 v74, v74, v75, s[16:17]
	v_fma_f32 v75, v183, v74, v191
	v_cndmask_b32_e64 v74, v74, v75, s[18:19]
	v_fma_f32 v75, v184, v74, v192
	v_cndmask_b32_e64 v74, v74, v75, s[20:21]
	v_fmac_f32_e32 v193, v185, v74
	v_cndmask_b32_e64 v74, v74, v193, s[38:39]
	s_waitcnt lgkmcnt(2)
	v_fma_f32 v75, v186, v74, v194
	v_cndmask_b32_e64 v74, v74, v75, s[22:23]
	v_fma_f32 v75, v187, v74, v195
	v_cndmask_b32_e64 v74, v74, v75, s[24:25]
	v_fma_f32 v75, v188, v74, v196
	v_cndmask_b32_e64 v74, v74, v75, s[26:27]
	v_fmac_f32_e32 v197, v189, v74
	v_mul_f32_e32 v76, 0xbfb8aa3b, v71
	v_cndmask_b32_e64 v74, v74, v197, s[4:5]
	v_exp_f32_e32 v76, v76
	s_waitcnt lgkmcnt(0)
	v_fma_f32 v75, v198, v74, v202
	v_cndmask_b32_e64 v74, v74, v75, s[28:29]
	v_fma_f32 v75, v199, v74, v203
	v_cndmask_b32_e64 v74, v74, v75, s[30:31]
	v_add_f32_e32 v75, 1.0, v76
	v_rcp_f32_e32 v75, v75
	v_fmac_f32_e32 v204, v200, v74
	v_cndmask_b32_e64 v74, v74, v204, s[34:35]
	v_fmac_f32_e32 v128, v82, v74
	v_mul_f32_e32 v71, v75, v71
	v_lshlrev_b32_e32 v75, 16, v70
	v_mul_f32_e32 v70, 0xbfb8aa3b, v75
	v_exp_f32_e32 v76, v70
	v_mul_f32_e32 v71, v71, v128
	v_add_co_u32_e32 v70, vcc, s36, v66
	v_cvt_pk_bf16_f32 v74, v71, s0
	s_nop 0
	v_addc_co_u32_e32 v71, vcc, 0, v67, vcc
	global_store_short v[70:71], v74, off
	v_add_f32_e32 v70, 1.0, v76
	v_rcp_f32_e32 v70, v70
	v_mul_f32_e32 v71, 0xbfb8aa3b, v69
	v_exp_f32_e32 v71, v71
	v_fmac_f32_e32 v73, v206, v128
	v_mul_f32_e32 v70, v70, v75
	v_mul_f32_e32 v70, v70, v73
	v_cvt_pk_bf16_f32 v74, v70, s0
	v_add_f32_e32 v70, 1.0, v71
	s_mov_b32 s36, 0x25c0c000
	v_rcp_f32_e32 v75, v70
	v_add_co_u32_e32 v70, vcc, s36, v66
	v_fmac_f32_e32 v124, v122, v73
	s_nop 0
	v_addc_co_u32_e32 v71, vcc, 0, v67, vcc
	global_store_short v[70:71], v74, off
	v_lshlrev_b32_e32 v70, 16, v68
	v_mul_f32_e32 v68, 0xbfb8aa3b, v70
	v_exp_f32_e32 v71, v68
	v_mul_f32_e32 v69, v75, v69
	v_mul_f32_e32 v69, v69, v124
	v_cvt_pk_bf16_f32 v73, v69, s0
	v_add_f32_e32 v69, 1.0, v71
	v_rcp_f32_e32 v71, v69
	s_mov_b32 s36, 0x25c18000
	v_add_co_u32_e32 v68, vcc, s36, v66
	v_fmac_f32_e32 v72, v207, v124
	s_nop 0
	v_addc_co_u32_e32 v69, vcc, 0, v67, vcc
	global_store_short v[68:69], v73, off
	v_mul_f32_e32 v68, v71, v70
	v_mul_f32_e32 v68, v68, v72
	s_mov_b64 s[100:101], 0x25c24000
	v_lshl_add_u64 v[66:67], v[66:67], 0, s[100:101]
	v_cvt_pk_bf16_f32 v68, v68, s0
	global_store_short v[66:67], v68, off
	s_and_saveexec_b64 s[36:37], s[34:35]
	s_cbranch_execz .LBB0_248
	ds_write_b32 v149, v72 offset:55360
	s_branch .LBB0_248

; #define LAS __attribute__((address_space(3)))
; DI float bf2f(unsigned h) { return __uint_as_float(h << 16); }
; DI float fexp2(float x) { return __builtin_amdgcn_exp2f(x); }
; DI float fsigmoid(float x) { return frcp(1.0f + fexp2(-LOG2E * x)); }
; DI void rglru_scan_unit(Frame& F, const Mix0Args& a, int u) {
;     ...
;         { bf16x8 xf[4], waf[4], wxf[4]; unsigned xcr[4];
; #pragma unroll
;           for (int ks = 0; ks < 4; ++ks) { xf[ks] = *(const LAS bf16x8*)(XCc + (l0_ + fr) * S128 + ks * 64 + fq * 16);
;               waf[ks] = *(const LAS bf16x8*)(WAT + (16 * jtile + fr) * S128 + ks * 64 + fq * 16); wxf[ks] = *(const LAS bf16x8*)(WXT + (16 * jtile + fr) * S128 + ks * 64 + fq * 16); }
; #pragma unroll
;           for (int r = 0; r < 4; ++r) xcr[r] = *(const LAS unsigned short*)(XCc + (l0_ + 4 * fq + r) * S128 + (qq * 32 + jj) * 2);
;           f32x4 R = zero4, I = zero4;
; #pragma unroll
;           for (int ks = 0; ks < 4; ++ks) { R = __builtin_amdgcn_mfma_f32_16x16x32_bf16(xf[ks], waf[ks], R, 0, 0, 0); I = __builtin_amdgcn_mfma_f32_16x16x32_bf16(xf[ks], wxf[ks], I, 0, 0, 0); }
; #pragma unroll
;           for (int r = 0; r < 4; ++r) {
;               const float rr = fsigmoid(R[r] + bav), ig = fsigmoid(I[r] + bxv);
;               const float aa = fexp2(-sp8l2 * rr); const float om = __builtin_fmaf(-aa, aa, 1.0f);
;               av[r] = aa; uv[r] = __builtin_sqrtf(om) * (ig * bf2f(xcr[r]));
;               Hseg = aa * Hseg + uv[r]; Aseg *= aa; } }
;         const int sgi = ltile * 4 + fq;
;         SEGA[jj * 20 + sgi] = Aseg; SEGH[jj * 20 + sgi] = Hseg;
.LBB0_328:
	s_and_b32 s77, s93, 1
	s_mul_i32 s36, s77, 0x1400
	s_add_i32 s78, s36, 0
	s_mul_i32 s36, s77, 0x3400
	s_add_i32 s36, s78, s36
	v_add3_u32 v38, s36, v143, v102
	ds_read_b128 v[14:17], v38
	ds_read_b128 v[18:21], v103 offset:36864
	ds_read_b128 v[22:25], v103 offset:36928
	ds_read_b128 v[26:29], v38 offset:64
	ds_read_b128 v[30:33], v103 offset:46080
	ds_read_b128 v[34:37], v103 offset:46144
	s_waitcnt lgkmcnt(4)
	v_mfma_f32_16x16x32_bf16 v[18:21], v[14:17], v[18:21], 0
	s_add_i32 s36, s36, s40
	v_add_u32_e32 v44, s78, v148
	s_waitcnt lgkmcnt(1)
	v_mfma_f32_16x16x32_bf16 v[14:17], v[14:17], v[30:33], 0
	v_mfma_f32_16x16x32_bf16 v[18:21], v[26:29], v[22:25], v[18:21]
	ds_read_b128 v[22:25], v38 offset:128
	ds_read_b128 v[30:33], v38 offset:192
	s_waitcnt lgkmcnt(2)
	v_mfma_f32_16x16x32_bf16 v[14:17], v[26:29], v[34:37], v[14:17]
	ds_read_b128 v[26:29], v103 offset:36992
	ds_read_b128 v[34:37], v103 offset:37056
	s_waitcnt lgkmcnt(1)
	v_mfma_f32_16x16x32_bf16 v[18:21], v[22:25], v[26:29], v[18:21]
	ds_read_b128 v[26:29], v103 offset:46208
	s_waitcnt lgkmcnt(1)
	v_mfma_f32_16x16x32_bf16 v[18:21], v[30:33], v[34:37], v[18:21]
	ds_read_b128 v[34:37], v103 offset:46272
	s_waitcnt lgkmcnt(1)
	v_mfma_f32_16x16x32_bf16 v[14:17], v[22:25], v[26:29], v[14:17]
	v_add3_u32 v22, s36, v144, v145
	s_nop 3
	v_add_f32_e32 v18, v165, v18
	v_mul_f32_e32 v18, 0xbfb8aa3b, v18
	v_exp_f32_e32 v18, v18
	s_waitcnt lgkmcnt(0)
	v_mfma_f32_16x16x32_bf16 v[14:17], v[30:33], v[34:37], v[14:17]
	v_add_f32_e32 v19, v165, v19
	v_mul_f32_e32 v19, 0xbfb8aa3b, v19
	v_add_f32_e32 v18, 1.0, v18
	v_rcp_f32_e32 v18, v18
	v_exp_f32_e32 v19, v19
	s_nop 2
	v_add_f32_e32 v14, v167, v14
	v_mul_f32_e32 v14, 0xbfb8aa3b, v14
	v_mul_f32_e64 v18, v18, -v168
	v_exp_f32_e32 v48, v18
	v_exp_f32_e32 v14, v14
	v_add_f32_e32 v19, 1.0, v19
	ds_read_u16 v24, v22
	ds_read_u16 v25, v22 offset:288
	ds_read_u16 v26, v22 offset:576
	ds_read_u16 v22, v22 offset:864
	v_fma_f32 v18, -v48, v48, 1.0
	s_nop 0
	s_nop 0
	v_add_f32_e32 v14, 1.0, v14
	v_rcp_f32_e32 v14, v14
	s_nop 0
	v_sqrt_f32_e32 v23, v18
	v_rcp_f32_e32 v19, v19
	v_add_f32_e32 v20, v165, v20
	v_mul_f32_e32 v20, 0xbfb8aa3b, v20
	v_add_u32_e32 v27, -1, v23
	v_add_u32_e32 v28, 1, v23
	v_fma_f32 v29, -v27, v23, v18
	v_fma_f32 v30, -v28, v23, v18
	v_cmp_ge_f32_e64 s[36:37], 0, v29
	v_exp_f32_e32 v20, v20
	v_add_f32_e32 v16, v167, v16
	v_cndmask_b32_e64 v23, v23, v27, s[36:37]
	v_cmp_lt_f32_e64 s[36:37], 0, v30
	v_add_f32_e32 v20, 1.0, v20
	v_rcp_f32_e32 v20, v20
	v_cndmask_b32_e64 v23, v23, v28, s[36:37]
	s_nop 0
	s_nop 0
	s_nop 0
	v_mul_f32_e32 v16, 0xbfb8aa3b, v16
	v_exp_f32_e32 v16, v16
	v_mov_b32_e32 v18, v23
	s_waitcnt lgkmcnt(3)
	v_lshlrev_b32_e32 v23, 16, v24
	v_mul_f32_e32 v14, v14, v23
	v_mul_f32_e32 v49, v14, v18
	v_mul_f32_e64 v14, v19, -v168
	s_waitcnt vmcnt(4)
	v_exp_f32_e32 v50, v14
	v_add_f32_e32 v14, v167, v15
	v_mul_f32_e32 v14, 0xbfb8aa3b, v14
	v_exp_f32_e32 v14, v14
	v_fma_f32 v15, -v50, v50, 1.0
	s_nop 0
	s_nop 0
	v_add_f32_e32 v14, 1.0, v14
	v_rcp_f32_e32 v14, v14
	s_nop 0
	v_sqrt_f32_e32 v18, v15
	v_fma_f32 v19, 0, v48, v49
	v_add_f32_e32 v21, v165, v21
	v_mul_f32_e32 v21, 0xbfb8aa3b, v21
	v_add_u32_e32 v23, -1, v18
	v_fma_f32 v24, -v23, v18, v15
	v_cmp_ge_f32_e64 s[36:37], 0, v24
	v_add_u32_e32 v24, 1, v18
	v_exp_f32_e32 v21, v21
	v_cndmask_b32_e64 v23, v18, v23, s[36:37]
	v_fma_f32 v18, -v24, v18, v15
	v_cmp_lt_f32_e64 s[36:37], 0, v18
	v_add_f32_e32 v16, 1.0, v16
	v_rcp_f32_e32 v16, v16
	v_cndmask_b32_e64 v18, v23, v24, s[36:37]
	s_nop 0
	s_nop 0
	s_nop 0
	v_add_f32_e32 v21, 1.0, v21
	v_rcp_f32_e32 v21, v21
	v_mov_b32_e32 v15, v18
	s_waitcnt lgkmcnt(2)
	v_lshlrev_b32_e32 v18, 16, v25
	v_mul_f32_e32 v14, v14, v18
	v_mul_f32_e64 v18, v20, -v168
	v_exp_f32_e32 v51, v18
	v_mul_f32_e32 v15, v14, v15
	v_fma_f32 v14, v50, v19, v15
	v_mul_f32_e32 v20, v48, v50
	v_fma_f32 v18, -v51, v51, 1.0
	s_nop 0
	s_nop 0
	s_nop 1
	s_nop 0
	v_sqrt_f32_e32 v19, v18
	s_nop 0
	v_add_u32_e32 v23, -1, v19
	v_fma_f32 v24, -v23, v19, v18
	v_cmp_ge_f32_e64 s[36:37], 0, v24
	v_add_u32_e32 v24, 1, v19
	s_nop 0
	v_cndmask_b32_e64 v23, v19, v23, s[36:37]
	v_fma_f32 v19, -v24, v19, v18
	v_cmp_lt_f32_e64 s[36:37], 0, v19
	s_nop 1
	v_cndmask_b32_e64 v19, v23, v24, s[36:37]
	s_nop 0
	s_nop 0
	s_nop 0
	s_nop 1
	v_mov_b32_e32 v18, v19
	s_waitcnt lgkmcnt(1)
	v_lshlrev_b32_e32 v19, 16, v26
	v_mul_f32_e32 v16, v16, v19
	v_mul_f32_e32 v52, v16, v18
	v_fma_f32 v16, v51, v14, v52
	v_mul_f32_e64 v14, v21, -v168
	v_exp_f32_e32 v53, v14
	v_add_f32_e32 v14, v167, v17
	v_mul_f32_e32 v14, 0xbfb8aa3b, v14
	v_exp_f32_e32 v14, v14
	v_fma_f32 v17, -v53, v53, 1.0
	s_nop 0
	s_nop 0
	v_mul_f32_e32 v19, v51, v20
	v_add_f32_e32 v14, 1.0, v14
	s_nop 0
	v_sqrt_f32_e32 v18, v17
	v_rcp_f32_e32 v14, v14
	v_add_u32_e32 v20, -1, v18
	v_fma_f32 v21, -v20, v18, v17
	v_cmp_ge_f32_e64 s[36:37], 0, v21
	v_add_u32_e32 v21, 1, v18
	s_nop 0
	v_cndmask_b32_e64 v20, v18, v20, s[36:37]
	v_fma_f32 v18, -v21, v18, v17
	v_cmp_lt_f32_e64 s[36:37], 0, v18
	s_nop 1
	v_cndmask_b32_e64 v18, v20, v21, s[36:37]
	s_nop 0
	s_nop 0
	s_nop 0
	s_nop 1
	v_mov_b32_e32 v17, v18
	s_waitcnt lgkmcnt(0)
	v_lshlrev_b32_e32 v18, 16, v22
	v_mul_f32_e32 v14, v14, v18
	v_mul_f32_e32 v14, v14, v17
	v_fma_f32 v16, v53, v16, v14
	v_mul_f32_e32 v17, v53, v19
	v_lshl_add_u32 v18, v147, 2, v44
	ds_write2st64_b32 v18, v17, v16 offset0:216 offset1:226
	s_waitcnt lgkmcnt(0)
	s_barrier
; #define LAS __attribute__((address_space(3)))
; DI float bf2f(unsigned h) { return __uint_as_float(h << 16); }
; DI unsigned pk2(float lo, float hi) { f32x2 v = {lo, hi}; bf16v2 b = __builtin_convertvector(v, bf16v2); return __builtin_bit_cast(unsigned, b); }
; DI float fsilu(float x) { return x * fsigmoid(x); }
; DI void rglru_scan_unit(Frame& F, const Mix0Args& a, int u) {
;     ...
;         float carry = HPREV[jj * 20 + (n & 1)]; float sa[15], sh[15];
;         { f32x4 a4[4], h4[4];
; #pragma unroll
;           for (int i = 0; i < 4; ++i) { a4[i] = *(const LAS f32x4*)(SEGA + jj * 20 + 4 * i); h4[i] = *(const LAS f32x4*)(SEGH + jj * 20 + 4 * i); }
; #pragma unroll
;           for (int s = 0; s < 15; ++s) { sa[s] = a4[s >> 2][s & 3]; sh[s] = h4[s >> 2][s & 3]; } }
; #pragma unroll
;         for (int s = 0; s < 15; ++s) carry = (s < sgi) ? sa[s] * carry + sh[s] : carry;
; #pragma unroll
;         for (int r = 0; r < 4; ++r) { carry = av[r] * carry + uv[r];
;             const float o = carry * fsilu(bf2f(gb_cur[r]));
;             obcol[(row0 + l0_ + 4 * fq + r) * a.out_ld] = (bf16)(pk2(o, 0.f) & 0xffffu); }
;         if (sgi == 15) HPREV[jj * 20 + ((n + 1) & 1)] = carry;
	v_lshl_add_u32 v16, s77, 2, v149
	ds_read_b32 v54, v16 offset:55360
	ds_read_b128 v[16:19], v44 offset:57856
	ds_read_b128 v[20:23], v44 offset:57872
	ds_read_b128 v[24:27], v44 offset:55296
	ds_read_b128 v[28:31], v44 offset:55312
	ds_read_b128 v[32:35], v44 offset:55328
	ds_read_b128 v[36:39], v44 offset:55344
	ds_read_b128 v[40:43], v44 offset:57888
	ds_read_b128 v[44:47], v44 offset:57904
	s_waitcnt lgkmcnt(5)
	v_fma_f32 v16, v54, v24, v16
	v_cndmask_b32_e64 v16, v16, v54, s[10:11]
	v_fma_f32 v17, v25, v16, v17
	v_cndmask_b32_e64 v16, v16, v17, s[12:13]
	v_fma_f32 v17, v26, v16, v18
	v_cndmask_b32_e64 v16, v16, v17, s[14:15]
	v_fmac_f32_e32 v19, v27, v16
	v_cndmask_b32_e64 v16, v19, v16, s[0:1]
	s_waitcnt lgkmcnt(4)
	v_fma_f32 v17, v28, v16, v20
	v_cndmask_b32_e64 v16, v16, v17, s[16:17]
	v_fma_f32 v17, v29, v16, v21
	v_cndmask_b32_e64 v16, v16, v17, s[18:19]
	v_fma_f32 v17, v30, v16, v22
	v_cndmask_b32_e64 v16, v16, v17, s[20:21]
	v_fmac_f32_e32 v23, v31, v16
	v_cndmask_b32_e64 v16, v16, v23, s[38:39]
	s_waitcnt lgkmcnt(1)
	v_fma_f32 v17, v32, v16, v40
	v_cndmask_b32_e64 v16, v16, v17, s[22:23]
	v_fma_f32 v17, v33, v16, v41
	v_cndmask_b32_e64 v16, v16, v17, s[24:25]
	v_fma_f32 v17, v34, v16, v42
	v_cndmask_b32_e64 v16, v16, v17, s[26:27]
	v_lshlrev_b32_e32 v18, 16, v181
	v_fmac_f32_e32 v43, v35, v16
	v_mul_f32_e32 v19, 0xbfb8aa3b, v18
	v_cndmask_b32_e64 v16, v16, v43, s[4:5]
	v_exp_f32_e32 v19, v19
	s_waitcnt lgkmcnt(0)
	v_fma_f32 v17, v36, v16, v44
	v_cndmask_b32_e64 v16, v16, v17, s[28:29]
	v_fma_f32 v17, v37, v16, v45
	v_cndmask_b32_e64 v16, v16, v17, s[30:31]
	v_add_f32_e32 v17, 1.0, v19
	v_rcp_f32_e32 v17, v17
	v_fmac_f32_e32 v46, v38, v16
	v_cndmask_b32_e64 v16, v16, v46, s[34:35]
	v_fmac_f32_e32 v49, v48, v16
	v_mul_f32_e32 v16, v17, v18
	v_or_b32_e32 v20, s82, v8
	v_mul_f32_e32 v16, v16, v49
	v_cvt_pk_bf16_f32 v21, v16, s0
	v_mad_u64_u32 v[16:17], s[36:37], v20, s33, v[2:3]
	v_or_b32_e32 v19, s83, v9
	v_mov_b32_e32 v18, v17
	v_mad_u64_u32 v[18:19], s[36:37], v19, s33, v[18:19]
	v_lshlrev_b32_e32 v19, 16, v180
	v_mul_f32_e32 v17, 0xbfb8aa3b, v19
	v_exp_f32_e32 v20, v17
	v_mov_b32_e32 v17, v18
	v_lshlrev_b32_e32 v22, 16, v179
	global_store_short v[16:17], v21, off
	v_add_f32_e32 v17, 1.0, v20
	v_mul_f32_e32 v20, 0xbfb8aa3b, v22
	v_rcp_f32_e32 v17, v17
	v_exp_f32_e32 v20, v20
	v_fmac_f32_e32 v15, v50, v49
	v_fmac_f32_e32 v52, v51, v15
	v_mul_f32_e32 v17, v17, v19
	v_add_f32_e32 v19, 1.0, v20
	v_rcp_f32_e32 v19, v19
	v_mul_f32_e32 v17, v17, v15
	v_add_co_u32_e32 v20, vcc, s33, v16
	v_cvt_pk_bf16_f32 v17, v17, s0
	s_nop 0
	v_addc_co_u32_e32 v21, vcc, 0, v18, vcc
	global_store_short v[20:21], v17, off
	v_lshlrev_b32_e32 v17, 16, v178
	v_mul_f32_e32 v15, v19, v22
	v_mul_f32_e32 v19, 0xbfb8aa3b, v17
	v_exp_f32_e32 v19, v19
	s_mov_b32 s36, 0x18000
	v_mul_f32_e32 v15, v15, v52
	v_add_co_u32_e32 v20, vcc, s36, v16
	v_add_f32_e32 v19, 1.0, v19
	v_rcp_f32_e32 v19, v19
	v_cvt_pk_bf16_f32 v15, v15, s0
	v_addc_co_u32_e32 v21, vcc, 0, v18, vcc
	global_store_short v[20:21], v15, off
	v_fmac_f32_e32 v14, v53, v52
	v_mul_f32_e32 v15, v19, v17
	v_mul_f32_e32 v15, v15, v14
	v_add_co_u32_e32 v16, vcc, 0x24000, v16
	v_cvt_pk_bf16_f32 v15, v15, s0
	s_nop 0
	v_addc_co_u32_e32 v17, vcc, 0, v18, vcc
	global_store_short v[16:17], v15, off
	s_and_saveexec_b64 s[36:37], s[34:35]
	s_cbranch_execz .LBB0_321
	v_lshl_add_u32 v15, s76, 2, v149
	ds_write_b32 v15, v14 offset:55360
	s_branch .LBB0_321
